# PT buffer re-laid out tile-blocked and lane-linear (contiguous 1 KiB per store/load instruction) between F9a and F9b
# baseline (speedup 1.0000x reference)
.LBB0_1577:
	v_lshrrev_b32_e32 v142, 6, v138
	v_lshrrev_b32_e32 v136, 5, v140
	v_lshlrev_b32_e32 v142, 9, v142
	v_lshl_add_u32 v142, v136, 7, v142
	v_lshl_add_u32 v142, s85, 10, v142
	v_lshl_add_u32 v142, s16, 13, v142
	v_and_b32_e32 v136, 15, v138
	v_and_b32_e32 v137, 24, v140
	v_lshl_or_b32 v136, v136, 5, v137
	v_ashrrev_i32_e32 v137, 31, v136
	v_ashrrev_i32_e32 v143, 31, v142
	v_lshl_add_u64 v[144:145], v[136:137], 1, s[10:11]
	v_lshlrev_b64 v[136:137], 7, v[142:143]
	v_lshl_add_u64 v[136:137], v[144:145], 0, v[136:137]
	v_cvt_pk_bf16_f32 v126, v126, v127
	v_cvt_pk_bf16_f32 v127, v128, v129
	v_cvt_pk_bf16_f32 v128, v122, v123
	v_cvt_pk_bf16_f32 v129, v124, v125
	global_store_dwordx4 v[136:137], v[126:129], off
	v_cvt_pk_bf16_f32 v114, v114, v115
	v_cvt_pk_bf16_f32 v115, v116, v117
	v_cvt_pk_bf16_f32 v116, v106, v107
	v_or_b32_e32 v106, 16, v142
	v_ashrrev_i32_e32 v107, 31, v106
	v_lshlrev_b64 v[106:107], 7, v[106:107]
	v_cvt_pk_bf16_f32 v117, v108, v109
	global_store_dwordx4 v[136:137], v[114:117], off offset:1024
	s_mov_b64 s[8:9], 0x2000
	v_readlane_b32 s86, v255, 14
	v_lshl_add_u64 v[114:115], v[144:145], 0, v[106:107]
	v_cvt_pk_bf16_f32 v106, v118, v119
	v_cvt_pk_bf16_f32 v107, v120, v121
	v_cvt_pk_bf16_f32 v108, v110, v111
	v_cvt_pk_bf16_f32 v109, v112, v113
	global_store_dwordx4 v[114:115], v[106:109], off
	v_cvt_pk_bf16_f32 v98, v98, v99
	v_cvt_pk_bf16_f32 v99, v100, v101
	v_cvt_pk_bf16_f32 v100, v90, v91
	v_or_b32_e32 v90, 32, v142
	v_ashrrev_i32_e32 v91, 31, v90
	v_lshlrev_b64 v[90:91], 7, v[90:91]
	v_cvt_pk_bf16_f32 v101, v92, v93
	global_store_dwordx4 v[114:115], v[98:101], off offset:1024
	v_readlane_b32 s88, v255, 16
	v_readlane_b32 s87, v255, 15
	v_lshl_add_u64 v[98:99], v[144:145], 0, v[90:91]
	v_cvt_pk_bf16_f32 v90, v102, v103
	v_cvt_pk_bf16_f32 v91, v104, v105
	v_cvt_pk_bf16_f32 v92, v94, v95
	v_cvt_pk_bf16_f32 v93, v96, v97
	global_store_dwordx4 v[98:99], v[90:93], off
	v_cvt_pk_bf16_f32 v82, v82, v83
	v_cvt_pk_bf16_f32 v83, v84, v85
	v_cvt_pk_bf16_f32 v84, v74, v75
	v_or_b32_e32 v74, 48, v142
	v_ashrrev_i32_e32 v75, 31, v74
	v_lshlrev_b64 v[74:75], 7, v[74:75]
	v_cvt_pk_bf16_f32 v85, v76, v77
	global_store_dwordx4 v[98:99], v[82:85], off offset:1024
	v_readlane_b32 s89, v255, 17
	s_nop 0
	v_lshl_add_u64 v[82:83], v[144:145], 0, v[74:75]
	v_cvt_pk_bf16_f32 v74, v86, v87
	v_cvt_pk_bf16_f32 v75, v88, v89
	v_cvt_pk_bf16_f32 v76, v78, v79
	v_cvt_pk_bf16_f32 v77, v80, v81
	global_store_dwordx4 v[82:83], v[74:77], off
	v_cvt_pk_bf16_f32 v70, v70, v71
	v_cvt_pk_bf16_f32 v71, v72, v73
	v_cvt_pk_bf16_f32 v72, v66, v67
	v_lshl_add_u64 v[66:67], v[136:137], 0, s[8:9]
	s_mov_b32 s8, 0x2000
	v_cvt_pk_bf16_f32 v73, v68, v69
	global_store_dwordx4 v[82:83], v[70:73], off offset:1024
	v_cvt_pk_bf16_f32 v62, v62, v63
	v_cvt_pk_bf16_f32 v63, v64, v65
	v_cvt_pk_bf16_f32 v64, v58, v59
	v_add_co_u32_e32 v58, vcc, s8, v136
	v_cvt_pk_bf16_f32 v65, v60, v61
	s_mov_b64 s[8:9], 0x2800
	s_nop 0
	v_addc_co_u32_e32 v59, vcc, 0, v137, vcc
	global_store_dwordx4 v[58:59], v[62:65], off
	v_cvt_pk_bf16_f32 v50, v50, v51
	v_cvt_pk_bf16_f32 v51, v52, v53
	v_cvt_pk_bf16_f32 v52, v42, v43
	v_cvt_pk_bf16_f32 v53, v44, v45
	global_store_dwordx4 v[66:67], v[50:53], off offset:1024
	v_cvt_pk_bf16_f32 v42, v54, v55
	v_cvt_pk_bf16_f32 v43, v56, v57
	v_cvt_pk_bf16_f32 v44, v46, v47
	v_cvt_pk_bf16_f32 v45, v48, v49
	s_nop 1
	v_lshl_add_u64 v[50:51], v[136:137], 0, s[8:9]
	s_mov_b32 s8, 0x2800
	v_add_co_u32_e32 v46, vcc, s8, v136
	s_mov_b64 s[8:9], 0x3000
	s_nop 0
	v_addc_co_u32_e32 v47, vcc, 0, v137, vcc
	global_store_dwordx4 v[46:47], v[42:45], off
	v_cvt_pk_bf16_f32 v34, v34, v35
	v_cvt_pk_bf16_f32 v35, v36, v37
	v_cvt_pk_bf16_f32 v36, v26, v27
	v_cvt_pk_bf16_f32 v37, v28, v29
	global_store_dwordx4 v[50:51], v[34:37], off offset:1024
	v_cvt_pk_bf16_f32 v26, v38, v39
	v_cvt_pk_bf16_f32 v27, v40, v41
	v_cvt_pk_bf16_f32 v28, v30, v31
	v_cvt_pk_bf16_f32 v29, v32, v33
	s_nop 1
	v_lshl_add_u64 v[34:35], v[136:137], 0, s[8:9]
	s_mov_b32 s8, 0x3000
	v_add_co_u32_e32 v30, vcc, s8, v136
	s_mov_b64 s[8:9], 0x3800
	s_nop 0
	v_addc_co_u32_e32 v31, vcc, 0, v137, vcc
	global_store_dwordx4 v[30:31], v[26:29], off
	v_cvt_pk_bf16_f32 v18, v18, v19
	v_cvt_pk_bf16_f32 v19, v20, v21
	v_cvt_pk_bf16_f32 v20, v10, v11
	v_cvt_pk_bf16_f32 v21, v12, v13
	global_store_dwordx4 v[34:35], v[18:21], off offset:1024
	v_cvt_pk_bf16_f32 v10, v22, v23
	v_cvt_pk_bf16_f32 v11, v24, v25
	v_cvt_pk_bf16_f32 v12, v14, v15
	v_cvt_pk_bf16_f32 v13, v16, v17
	s_nop 1
	v_lshl_add_u64 v[18:19], v[136:137], 0, s[8:9]
	s_mov_b32 s8, 0x3800
	v_add_co_u32_e32 v14, vcc, s8, v136
	s_nop 1
	v_addc_co_u32_e32 v15, vcc, 0, v137, vcc
	s_and_b64 vcc, exec, s[4:5]
	s_mov_b64 s[4:5], -1
	global_store_dwordx4 v[14:15], v[10:13], off
	v_cvt_pk_bf16_f32 v6, v6, v7
	v_cvt_pk_bf16_f32 v7, v8, v9
	v_cvt_pk_bf16_f32 v8, v2, v3
	v_cvt_pk_bf16_f32 v9, v4, v5
	global_store_dwordx4 v[18:19], v[6:9], off offset:1024
	s_cbranch_vccnz .LBB0_1559
	s_andn2_b64 vcc, exec, s[14:15]
	s_cbranch_vccnz .LBB0_1558
	s_barrier
	s_branch .LBB0_1558

.LBB0_1618:
	v_and_b32_e32 v67, 64, v218
	v_xor_b32_e32 v66, 16, v218
	v_add_u32_e32 v67, 64, v67
	s_mul_i32 s25, s89, 0x1400
	v_cmp_lt_i32_e32 vcc, v66, v67
	s_add_i32 s25, s25, 0
	s_add_i32 s25, s25, 0x20940
	v_cndmask_b32_e32 v66, v218, v66, vcc
	v_lshlrev_b32_e32 v223, 2, v66
	v_xor_b32_e32 v66, 32, v218
	v_cmp_lt_i32_e32 vcc, v66, v67
	v_add_u32_e32 v225, s25, v216
	v_add_u32_e32 v226, 0x800, v225
	v_cndmask_b32_e32 v70, v218, v66, vcc
	ds_read2_b64 v[66:69], v225 offset1:16
	v_lshlrev_b32_e32 v224, 2, v70
	ds_read2_b64 v[70:73], v226 offset1:16
	ds_read2_b64 v[138:141], v225 offset0:32 offset1:48
	ds_read2_b64 v[142:145], v226 offset0:32 offset1:48
	v_lshl_add_u32 v186, s60, 8, v197
	s_waitcnt lgkmcnt(0)
	v_cvt_f32_u32_e32 v67, v67
	v_cvt_f32_u32_e32 v71, v71
	v_cvt_f32_u32_e32 v70, v70
	v_cvt_f32_u32_e32 v66, v66
	v_cvt_f32_u32_e32 v69, v69
	v_cvt_f32_u32_e32 v68, v68
	v_fmac_f32_e32 v70, 0x4f800000, v71
	v_fmac_f32_e32 v66, 0x4f800000, v67
	v_fmamk_f32 v67, v70, 0x30000000, v1
	v_rsq_f32_e32 v70, v67
	v_cvt_f32_u32_e32 v72, v72
	v_fmamk_f32 v66, v66, 0x30000000, v1
	v_fmac_f32_e32 v68, 0x4f800000, v69
	v_mul_f32_e32 v67, v67, v70
	v_cvt_f32_u32_e32 v70, v73
	v_rsq_f32_e32 v66, v66
	v_fmamk_f32 v68, v68, 0x30000000, v1
	v_rsq_f32_e32 v68, v68
	v_fmac_f32_e32 v72, 0x4f800000, v70
	v_fmamk_f32 v69, v72, 0x30000000, v1
	v_rsq_f32_e32 v70, v69
	v_mul_f32_e32 v71, 0x3d214285, v66
	v_mul_f32_e32 v230, v71, v67
	v_mul_f32_e32 v200, 0x41cb3333, v66
	v_mul_f32_e32 v66, 0x3d214285, v68
	v_mul_f32_e32 v67, v69, v70
	v_mul_f32_e32 v229, v66, v67
	v_cvt_f32_u32_e32 v66, v139
	v_cvt_f32_u32_e32 v67, v138
	v_mul_f32_e32 v198, 0x41cb3333, v68
	v_cvt_f32_u32_e32 v68, v143
	v_cvt_f32_u32_e32 v69, v142
	v_fmac_f32_e32 v67, 0x4f800000, v66
	v_fmamk_f32 v66, v67, 0x30000000, v1
	v_cvt_f32_u32_e32 v70, v141
	v_fmac_f32_e32 v69, 0x4f800000, v68
	v_fmamk_f32 v67, v69, 0x30000000, v1
	v_rsq_f32_e32 v68, v67
	v_cvt_f32_u32_e32 v71, v140
	v_cvt_f32_u32_e32 v72, v144
	v_rsq_f32_e32 v66, v66
	v_mul_f32_e32 v67, v67, v68
	v_cvt_f32_u32_e32 v68, v145
	v_fmac_f32_e32 v71, 0x4f800000, v70
	v_fmamk_f32 v70, v71, 0x30000000, v1
	v_lshl_or_b32 v182, s62, 8, v217
	v_fmac_f32_e32 v72, 0x4f800000, v68
	v_fmamk_f32 v68, v72, 0x30000000, v1
	v_rsq_f32_e32 v70, v70
	v_rsq_f32_e32 v71, v68
	v_ashrrev_i32_e32 v187, 31, v186
	v_ashrrev_i32_e32 v183, 31, v182
	v_lshlrev_b64 v[202:203], 11, v[186:187]
	s_lshl_b32 s26, s81, 2
	v_lshl_add_u64 v[138:139], v[202:203], 0, v[182:183]
	s_add_i32 s26, s25, s26
	v_mul_f32_e32 v69, 0x3d214285, v66
	v_lshlrev_b64 v[138:139], 1, v[138:139]
	v_lshl_add_u32 v231, v199, 2, s26
	v_mul_f32_e32 v228, v69, v67
	v_mul_f32_e32 v196, 0x41cb3333, v66
	v_mul_f32_e32 v66, 0x3d214285, v70
	v_mul_f32_e32 v67, v68, v71
	v_lshrrev_b32_e32 v250, 6, v197
	v_lshrrev_b32_e32 v251, 5, v217
	v_lshlrev_b32_e32 v250, 9, v250
	v_lshl_add_u32 v250, v251, 7, v250
	v_lshl_add_u32 v250, s62, 10, v250
	v_lshl_add_u32 v250, s60, 13, v250
	v_lshlrev_b32_e32 v250, 7, v250
	v_and_b32_e32 v251, 15, v197
	v_lshl_add_u32 v250, v251, 6, v250
	v_and_b32_e32 v251, 24, v217
	v_lshl_add_u32 v250, v251, 1, v250
	v_mov_b32_e32 v251, 0
	v_lshl_add_u64 v[242:243], v[250:251], 0, s[10:11]
	s_mov_b32 s100, 0x1000
	s_mov_b32 s101, 0
	v_lshl_add_u64 v[244:245], v[242:243], 0, s[100:101]
	v_lshl_add_u64 v[246:247], v[244:245], 0, s[100:101]
	v_lshl_add_u64 v[248:249], v[246:247], 0, s[100:101]
	v_lshl_add_u64 v[140:141], s[14:15], 0, v[138:139]
	v_mul_f32_e32 v227, v66, v67
	v_mul_f32_e32 v194, 0x41cb3333, v70
	ds_read_b128 v[70:73], v231 offset:4096
	ds_read_b128 v[66:69], v231 offset:4112
	global_load_dwordx4 v[210:213], v[140:141], off
	v_lshl_add_u64 v[138:139], s[10:11], 0, v[138:139]
	global_load_dwordx4 v[232:235], v[242:243], off
	v_or_b32_e32 v192, 16, v186
	v_ashrrev_i32_e32 v193, 31, v192
	v_lshlrev_b64 v[204:205], 11, v[192:193]
	v_lshl_add_u64 v[138:139], v[204:205], 0, v[182:183]
	v_lshlrev_b64 v[138:139], 1, v[138:139]
	v_lshl_add_u64 v[140:141], s[14:15], 0, v[138:139]
	global_load_dwordx4 v[158:161], v[140:141], off
	v_lshl_add_u64 v[138:139], s[10:11], 0, v[138:139]
	global_load_dwordx4 v[154:157], v[242:243], off offset:2048
	v_or_b32_e32 v190, 32, v186
	v_ashrrev_i32_e32 v191, 31, v190
	v_lshlrev_b64 v[206:207], 11, v[190:191]
	v_cvt_f32_i32_e32 v134, v134
	v_cvt_f32_i32_e32 v130, v130
	v_lshl_add_u64 v[138:139], v[206:207], 0, v[182:183]
	v_lshlrev_b64 v[138:139], 1, v[138:139]
	v_lshl_add_u64 v[140:141], s[14:15], 0, v[138:139]
	global_load_dwordx4 v[150:153], v[140:141], off
	v_mul_f32_e32 v134, v230, v134
	v_mul_f32_e32 v130, v230, v130
	v_cvt_f32_i32_e32 v135, v135
	v_cvt_f32_i32_e32 v131, v131
	s_waitcnt lgkmcnt(0)
	v_mul_f32_e32 v134, v70, v134
	v_mul_f32_e32 v130, v66, v130
	v_lshl_add_u64 v[138:139], s[10:11], 0, v[138:139]
	v_mul_f32_e32 v134, 0xbfb8aa3b, v134
	v_mul_f32_e32 v130, 0xbfb8aa3b, v130
	global_load_dwordx4 v[146:149], v[244:245], off
	v_exp_f32_e32 v134, v134
	v_exp_f32_e32 v168, v130
	v_mul_f32_e32 v135, v230, v135
	v_mul_f32_e32 v131, v230, v131
	v_cvt_f32_i32_e32 v136, v136
	v_cvt_f32_i32_e32 v132, v132
	v_mul_f32_e32 v135, v71, v135
	v_mul_f32_e32 v131, v67, v131
	v_mul_f32_e32 v135, 0xbfb8aa3b, v135
	v_mul_f32_e32 v131, 0xbfb8aa3b, v131
	v_add_f32_e32 v130, 1.0, v134
	v_add_f32_e32 v134, 1.0, v168
	v_exp_f32_e32 v135, v135
	v_exp_f32_e32 v168, v131
	v_mul_f32_e32 v136, v230, v136
	v_mul_f32_e32 v132, v230, v132
	v_cvt_f32_i32_e32 v137, v137
	v_cvt_f32_i32_e32 v133, v133
	v_mul_f32_e32 v136, v72, v136
	v_mul_f32_e32 v132, v68, v132
	v_mul_f32_e32 v136, 0xbfb8aa3b, v136
	v_mul_f32_e32 v132, 0xbfb8aa3b, v132
	v_add_f32_e32 v131, 1.0, v135
	v_add_f32_e32 v135, 1.0, v168
	v_exp_f32_e32 v136, v136
	v_exp_f32_e32 v168, v132
	v_mul_f32_e32 v137, v230, v137
	v_mul_f32_e32 v133, v230, v133
	v_mul_f32_e32 v137, v73, v137
	v_mul_f32_e32 v133, v69, v133
	v_mul_f32_e32 v137, 0xbfb8aa3b, v137
	v_mul_f32_e32 v133, 0xbfb8aa3b, v133
	v_add_f32_e32 v132, 1.0, v136
	v_add_f32_e32 v136, 1.0, v168
	v_exp_f32_e32 v137, v137
	v_exp_f32_e32 v168, v133
	v_rcp_f32_e32 v130, v130
	v_rcp_f32_e32 v131, v131
	v_add_f32_e32 v133, 1.0, v137
	v_add_f32_e32 v137, 1.0, v168
	v_rcp_f32_e32 v132, v132
	v_rcp_f32_e32 v133, v133
	v_or_b32_e32 v188, 48, v186
	v_rcp_f32_e32 v134, v134
	v_rcp_f32_e32 v135, v135
	v_ashrrev_i32_e32 v189, 31, v188
	v_lshlrev_b64 v[208:209], 11, v[188:189]
	v_rcp_f32_e32 v136, v136
	v_rcp_f32_e32 v137, v137
	s_waitcnt vmcnt(0)
	v_cvt_f32_f16_e32 v168, v210
	v_cvt_f32_f16_sdwa v169, v210 dst_sel:DWORD dst_unused:UNUSED_PAD src0_sel:WORD_1
	v_cvt_f32_f16_e32 v170, v211
	v_cvt_f32_f16_sdwa v171, v211 dst_sel:DWORD dst_unused:UNUSED_PAD src0_sel:WORD_1
	v_lshlrev_b32_e32 v184, 16, v232
	v_and_b32_e32 v185, 0xffff0000, v232
	v_pk_fma_f32 v[168:169], v[130:131], v[184:185], v[168:169]
	v_cvt_f32_f16_e32 v130, v212
	v_cvt_f32_f16_sdwa v131, v212 dst_sel:DWORD dst_unused:UNUSED_PAD src0_sel:WORD_1
	v_lshlrev_b32_e32 v210, 16, v233
	v_and_b32_e32 v211, 0xffff0000, v233
	v_pk_fma_f32 v[170:171], v[132:133], v[210:211], v[170:171]
	v_cvt_f32_f16_e32 v132, v213
	v_cvt_f32_f16_sdwa v133, v213 dst_sel:DWORD dst_unused:UNUSED_PAD src0_sel:WORD_1
	v_lshl_add_u64 v[138:139], v[208:209], 0, v[182:183]
	v_lshlrev_b32_e32 v184, 16, v234
	v_and_b32_e32 v185, 0xffff0000, v234
	v_lshlrev_b64 v[138:139], 1, v[138:139]
	v_pk_fma_f32 v[212:213], v[134:135], v[184:185], v[130:131]
	v_lshlrev_b64 v[130:131], 12, v[186:187]
	v_lshl_add_u64 v[140:141], s[14:15], 0, v[138:139]
	v_lshlrev_b32_e32 v210, 16, v235
	v_and_b32_e32 v211, 0xffff0000, v235
	v_lshl_add_u64 v[130:131], s[16:17], 0, v[130:131]
	v_lshlrev_b64 v[184:185], 1, v[182:183]
	global_load_dwordx4 v[142:145], v[140:141], off
	v_pk_fma_f32 v[136:137], v[136:137], v[210:211], v[132:133]
	v_cvt_pk_f16_f32 v132, v168, v169
	v_lshl_add_u64 v[210:211], v[130:131], 0, v[184:185]
	v_mov_b32_e32 v130, 0
	v_cvt_pk_f16_f32 v133, v170, v171
	v_dot2c_f32_f16_e32 v130, v132, v132
	v_lshl_add_u64 v[138:139], s[10:11], 0, v[138:139]
	v_cvt_pk_f16_f32 v134, v212, v213
	v_dot2c_f32_f16_e32 v130, v133, v133
	v_cvt_f32_i32_e32 v126, v126
	v_cvt_f32_i32_e32 v122, v122
	global_load_dwordx4 v[138:141], v[244:245], off offset:2048
	v_cvt_pk_f16_f32 v135, v136, v137
	v_dot2c_f32_f16_e32 v130, v134, v134
	global_store_dwordx4 v[210:211], v[132:135], off
	v_dot2c_f32_f16_e32 v130, v135, v135
	v_pk_fma_f32 v[136:137], v[200:201], v[136:137], s[42:43] op_sel_hi:[0,1,0]
	v_pk_fma_f32 v[132:133], v[200:201], v[168:169], s[42:43] op_sel_hi:[0,1,0]
	v_pk_fma_f32 v[134:135], v[200:201], v[170:171], s[42:43] op_sel_hi:[0,1,0]
	v_med3_f32 v131, v132, s93, v221
	v_med3_f32 v132, v133, s93, v221
	v_med3_f32 v133, v134, s93, v221
	v_med3_f32 v134, v135, s93, v221
	v_perm_b32 v133, v134, v133, s1
	v_perm_b32 v131, v132, v131, s1
	v_pk_fma_f32 v[134:135], v[200:201], v[212:213], s[42:43] op_sel_hi:[0,1,0]
	v_mul_f32_e32 v126, v229, v126
	v_mul_f32_e32 v122, v229, v122
	v_cvt_f32_i32_e32 v127, v127
	v_cvt_f32_i32_e32 v123, v123
	v_perm_b32 v132, v133, v131, s51
	v_med3_f32 v131, v134, s93, v221
	v_med3_f32 v133, v135, s93, v221
	v_med3_f32 v134, v136, s93, v221
	v_med3_f32 v135, v137, s93, v221
	v_mul_f32_e32 v126, v70, v126
	v_mul_f32_e32 v122, v66, v122
	v_perm_b32 v134, v135, v134, s1
	v_perm_b32 v131, v133, v131, s1
	v_mul_f32_e32 v126, 0xbfb8aa3b, v126
	v_mul_f32_e32 v122, 0xbfb8aa3b, v122
	v_perm_b32 v133, v134, v131, s51
	v_exp_f32_e32 v126, v126
	v_exp_f32_e32 v131, v122
	v_mul_f32_e32 v127, v229, v127
	v_mul_f32_e32 v123, v229, v123
	v_cvt_f32_i32_e32 v128, v128
	v_cvt_f32_i32_e32 v124, v124
	v_cvt_f32_i32_e32 v129, v129
	v_mul_f32_e32 v127, v71, v127
	v_mul_f32_e32 v123, v67, v123
	v_mul_f32_e32 v127, 0xbfb8aa3b, v127
	v_mul_f32_e32 v123, 0xbfb8aa3b, v123
	v_add_f32_e32 v122, 1.0, v126
	v_add_f32_e32 v126, 1.0, v131
	v_exp_f32_e32 v127, v127
	v_exp_f32_e32 v131, v123
	v_mul_f32_e32 v128, v229, v128
	v_mul_f32_e32 v124, v229, v124
	v_mul_f32_e32 v129, v229, v129
	v_cvt_f32_i32_e32 v125, v125
	v_mul_f32_e32 v128, v72, v128
	v_mul_f32_e32 v124, v68, v124
	v_mul_f32_e32 v129, v73, v129
	v_mul_f32_e32 v128, 0xbfb8aa3b, v128
	v_mul_f32_e32 v124, 0xbfb8aa3b, v124
	v_mul_f32_e32 v129, 0xbfb8aa3b, v129
	v_add_f32_e32 v123, 1.0, v127
	v_add_f32_e32 v127, 1.0, v131
	v_exp_f32_e32 v128, v128
	v_exp_f32_e32 v131, v124
	v_exp_f32_e32 v129, v129
	v_mul_f32_e32 v125, v229, v125
	v_mul_f32_e32 v125, v69, v125
	v_lshl_add_u64 v[134:135], s[20:21], 0, v[202:203]
	v_mul_f32_e32 v125, 0xbfb8aa3b, v125
	v_lshl_add_u64 v[212:213], v[134:135], 0, v[182:183]
	v_add_f32_e32 v124, 1.0, v128
	v_add_f32_e32 v128, 1.0, v131
	v_exp_f32_e32 v131, v125
	v_add_f32_e32 v125, 1.0, v129
	global_store_dwordx2 v[212:213], v[132:133], off
	v_rcp_f32_e32 v122, v122
	v_rcp_f32_e32 v123, v123
	v_rcp_f32_e32 v124, v124
	v_rcp_f32_e32 v125, v125
	v_cvt_f32_f16_e32 v132, v158
	v_cvt_f32_f16_sdwa v133, v158 dst_sel:DWORD dst_unused:UNUSED_PAD src0_sel:WORD_1
	v_cvt_f32_f16_e32 v134, v159
	v_cvt_f32_f16_sdwa v135, v159 dst_sel:DWORD dst_unused:UNUSED_PAD src0_sel:WORD_1
	v_add_f32_e32 v129, 1.0, v131
	v_lshlrev_b32_e32 v136, 16, v154
	v_and_b32_e32 v137, 0xffff0000, v154
	v_lshlrev_b32_e32 v154, 16, v155
	v_and_b32_e32 v155, 0xffff0000, v155
	v_rcp_f32_e32 v126, v126
	v_rcp_f32_e32 v127, v127
	v_rcp_f32_e32 v128, v128
	v_rcp_f32_e32 v129, v129
	v_pk_fma_f32 v[134:135], v[124:125], v[154:155], v[134:135]
	v_pk_fma_f32 v[132:133], v[122:123], v[136:137], v[132:133]
	v_cvt_f32_f16_e32 v122, v160
	v_cvt_f32_f16_sdwa v123, v160 dst_sel:DWORD dst_unused:UNUSED_PAD src0_sel:WORD_1
	v_cvt_f32_f16_e32 v124, v161
	v_cvt_f32_f16_sdwa v125, v161 dst_sel:DWORD dst_unused:UNUSED_PAD src0_sel:WORD_1
	v_cvt_f32_i32_e32 v118, v118
	v_cvt_f32_i32_e32 v114, v114
	v_lshlrev_b32_e32 v136, 16, v156
	v_and_b32_e32 v137, 0xffff0000, v156
	v_lshlrev_b32_e32 v154, 16, v157
	v_and_b32_e32 v155, 0xffff0000, v157
	v_pk_fma_f32 v[128:129], v[128:129], v[154:155], v[124:125]
	v_pk_fma_f32 v[126:127], v[126:127], v[136:137], v[122:123]
	v_cvt_pk_f16_f32 v122, v132, v133
	v_cvt_pk_f16_f32 v123, v134, v135
	v_cvt_pk_f16_f32 v124, v126, v127
	v_cvt_pk_f16_f32 v125, v128, v129
	v_pk_fma_f32 v[132:133], v[198:199], v[132:133], s[42:43] op_sel_hi:[0,1,0]
	v_pk_fma_f32 v[134:135], v[198:199], v[134:135], s[42:43] op_sel_hi:[0,1,0]
	v_pk_fma_f32 v[126:127], v[198:199], v[126:127], s[42:43] op_sel_hi:[0,1,0]
	v_pk_fma_f32 v[128:129], v[198:199], v[128:129], s[42:43] op_sel_hi:[0,1,0]
	v_med3_f32 v131, v132, s93, v221
	v_med3_f32 v132, v133, s93, v221
	v_med3_f32 v133, v134, s93, v221
	v_med3_f32 v134, v135, s93, v221
	v_med3_f32 v126, v126, s93, v221
	v_med3_f32 v127, v127, s93, v221
	v_med3_f32 v128, v128, s93, v221
	v_med3_f32 v129, v129, s93, v221
	v_mul_f32_e32 v118, v228, v118
	v_mul_f32_e32 v114, v228, v114
	v_cvt_f32_i32_e32 v119, v119
	v_cvt_f32_i32_e32 v115, v115
	v_perm_b32 v133, v134, v133, s1
	v_perm_b32 v131, v132, v131, s1
	v_perm_b32 v128, v129, v128, s1
	v_perm_b32 v126, v127, v126, s1
	v_mul_f32_e32 v118, v70, v118
	v_mul_f32_e32 v114, v66, v114
	v_perm_b32 v132, v133, v131, s51
	v_perm_b32 v133, v128, v126, s51
	v_lshl_add_u64 v[126:127], s[20:21], 0, v[204:205]
	v_mul_f32_e32 v118, 0xbfb8aa3b, v118
	v_mul_f32_e32 v114, 0xbfb8aa3b, v114
	v_lshl_add_u64 v[156:157], v[126:127], 0, v[182:183]
	v_exp_f32_e32 v118, v118
	v_exp_f32_e32 v126, v114
	v_mul_f32_e32 v119, v228, v119
	v_mul_f32_e32 v115, v228, v115
	v_cvt_f32_i32_e32 v120, v120
	v_cvt_f32_i32_e32 v116, v116
	v_mul_f32_e32 v119, v71, v119
	v_mul_f32_e32 v115, v67, v115
	v_mul_f32_e32 v119, 0xbfb8aa3b, v119
	v_mul_f32_e32 v115, 0xbfb8aa3b, v115
	v_add_f32_e32 v114, 1.0, v118
	v_add_f32_e32 v118, 1.0, v126
	v_exp_f32_e32 v119, v119
	v_exp_f32_e32 v126, v115
	v_cvt_f32_i32_e32 v121, v121
	v_mul_f32_e32 v120, v228, v120
	v_mul_f32_e32 v116, v228, v116
	v_cvt_f32_i32_e32 v117, v117
	v_mul_f32_e32 v120, v72, v120
	v_mul_f32_e32 v116, v68, v116
	v_mul_f32_e32 v120, 0xbfb8aa3b, v120
	v_mul_f32_e32 v116, 0xbfb8aa3b, v116
	v_add_f32_e32 v115, 1.0, v119
	v_add_f32_e32 v119, 1.0, v126
	v_exp_f32_e32 v120, v120
	v_exp_f32_e32 v126, v116
	v_mul_f32_e32 v121, v228, v121
	v_mul_f32_e32 v121, v73, v121
	v_mul_f32_e32 v117, v228, v117
	v_mul_f32_e32 v121, 0xbfb8aa3b, v121
	v_mul_f32_e32 v117, v69, v117
	v_exp_f32_e32 v121, v121
	v_mul_f32_e32 v117, 0xbfb8aa3b, v117
	v_add_f32_e32 v116, 1.0, v120
	v_add_f32_e32 v120, 1.0, v126
	v_exp_f32_e32 v126, v117
	v_add_f32_e32 v117, 1.0, v121
	v_lshlrev_b64 v[136:137], 12, v[192:193]
	v_rcp_f32_e32 v114, v114
	v_rcp_f32_e32 v115, v115
	v_rcp_f32_e32 v116, v116
	v_rcp_f32_e32 v117, v117
	v_add_f32_e32 v121, 1.0, v126
	v_cvt_f32_f16_e32 v126, v150
	v_cvt_f32_f16_sdwa v127, v150 dst_sel:DWORD dst_unused:UNUSED_PAD src0_sel:WORD_1
	v_cvt_f32_f16_e32 v128, v151
	v_cvt_f32_f16_sdwa v129, v151 dst_sel:DWORD dst_unused:UNUSED_PAD src0_sel:WORD_1
	v_lshl_add_u64 v[136:137], s[16:17], 0, v[136:137]
	v_lshl_add_u64 v[154:155], v[136:137], 0, v[184:185]
	global_store_dwordx4 v[154:155], v[122:125], off
	global_store_dwordx2 v[156:157], v[132:133], off
	v_lshlrev_b32_e32 v132, 16, v146
	v_and_b32_e32 v133, 0xffff0000, v146
	v_lshlrev_b32_e32 v134, 16, v147
	v_and_b32_e32 v135, 0xffff0000, v147
	v_rcp_f32_e32 v118, v118
	v_rcp_f32_e32 v119, v119
	v_rcp_f32_e32 v120, v120
	v_rcp_f32_e32 v121, v121
	v_pk_fma_f32 v[128:129], v[116:117], v[134:135], v[128:129]
	v_pk_fma_f32 v[126:127], v[114:115], v[132:133], v[126:127]
	v_cvt_f32_f16_e32 v114, v152
	v_cvt_f32_f16_sdwa v115, v152 dst_sel:DWORD dst_unused:UNUSED_PAD src0_sel:WORD_1
	v_cvt_f32_f16_e32 v116, v153
	v_cvt_f32_f16_sdwa v117, v153 dst_sel:DWORD dst_unused:UNUSED_PAD src0_sel:WORD_1
	v_cvt_f32_i32_e32 v78, v78
	v_cvt_f32_i32_e32 v74, v74
	v_lshlrev_b32_e32 v132, 16, v148
	v_and_b32_e32 v133, 0xffff0000, v148
	v_lshlrev_b32_e32 v134, 16, v149
	v_and_b32_e32 v135, 0xffff0000, v149
	v_pk_fma_f32 v[120:121], v[120:121], v[134:135], v[116:117]
	v_pk_fma_f32 v[118:119], v[118:119], v[132:133], v[114:115]
	v_cvt_pk_f16_f32 v117, v120, v121
	v_cvt_pk_f16_f32 v116, v118, v119
	v_pk_fma_f32 v[118:119], v[196:197], v[118:119], s[42:43] op_sel_hi:[0,1,0]
	v_pk_fma_f32 v[120:121], v[196:197], v[120:121], s[42:43] op_sel_hi:[0,1,0]
	v_cvt_pk_f16_f32 v114, v126, v127
	v_pk_fma_f32 v[126:127], v[196:197], v[126:127], s[42:43] op_sel_hi:[0,1,0]
	v_med3_f32 v118, v118, s93, v221
	v_med3_f32 v119, v119, s93, v221
	v_med3_f32 v120, v120, s93, v221
	v_med3_f32 v121, v121, s93, v221
	v_mul_f32_e32 v78, v227, v78
	v_mul_f32_e32 v74, v227, v74
	v_cvt_f32_i32_e32 v79, v79
	v_cvt_f32_i32_e32 v75, v75
	v_med3_f32 v126, v126, s93, v221
	v_med3_f32 v127, v127, s93, v221
	v_perm_b32 v120, v121, v120, s1
	v_perm_b32 v118, v119, v118, s1
	v_mul_f32_e32 v78, v70, v78
	v_mul_f32_e32 v74, v66, v74
	v_perm_b32 v126, v127, v126, s1
	v_perm_b32 v127, v120, v118, s51
	v_lshl_add_u64 v[118:119], s[20:21], 0, v[206:207]
	v_mul_f32_e32 v78, 0xbfb8aa3b, v78
	v_mul_f32_e32 v74, 0xbfb8aa3b, v74
	v_lshl_add_u64 v[160:161], v[118:119], 0, v[182:183]
	v_exp_f32_e32 v78, v78
	v_exp_f32_e32 v118, v74
	v_mul_f32_e32 v79, v227, v79
	v_mul_f32_e32 v75, v227, v75
	v_cvt_f32_i32_e32 v80, v80
	v_cvt_f32_i32_e32 v76, v76
	v_mul_f32_e32 v79, v71, v79
	v_mul_f32_e32 v75, v67, v75
	v_mul_f32_e32 v79, 0xbfb8aa3b, v79
	v_mul_f32_e32 v75, 0xbfb8aa3b, v75
	v_add_f32_e32 v74, 1.0, v78
	v_add_f32_e32 v78, 1.0, v118
	v_exp_f32_e32 v79, v79
	v_exp_f32_e32 v118, v75
	v_mul_f32_e32 v80, v227, v80
	v_mul_f32_e32 v76, v227, v76
	v_cvt_f32_i32_e32 v81, v81
	v_cvt_f32_i32_e32 v77, v77
	v_mul_f32_e32 v80, v72, v80
	v_mul_f32_e32 v76, v68, v76
	v_mul_f32_e32 v80, 0xbfb8aa3b, v80
	v_mul_f32_e32 v76, 0xbfb8aa3b, v76
	v_add_f32_e32 v75, 1.0, v79
	v_add_f32_e32 v79, 1.0, v118
	v_exp_f32_e32 v80, v80
	v_exp_f32_e32 v118, v76
	v_mul_f32_e32 v81, v227, v81
	v_mul_f32_e32 v77, v227, v77
	v_mul_f32_e32 v81, v73, v81
	v_mul_f32_e32 v77, v69, v77
	v_mul_f32_e32 v81, 0xbfb8aa3b, v81
	v_mul_f32_e32 v77, 0xbfb8aa3b, v77
	v_add_f32_e32 v76, 1.0, v80
	v_add_f32_e32 v80, 1.0, v118
	v_exp_f32_e32 v81, v81
	v_exp_f32_e32 v118, v77
	v_cvt_pk_f16_f32 v115, v128, v129
	v_pk_fma_f32 v[128:129], v[196:197], v[128:129], s[42:43] op_sel_hi:[0,1,0]
	v_lshlrev_b64 v[132:133], 12, v[190:191]
	v_med3_f32 v128, v128, s93, v221
	v_med3_f32 v129, v129, s93, v221
	v_rcp_f32_e32 v74, v74
	v_rcp_f32_e32 v75, v75
	v_add_f32_e32 v77, 1.0, v81
	v_add_f32_e32 v81, 1.0, v118
	s_waitcnt vmcnt(5)
	v_cvt_f32_f16_e32 v118, v142
	v_cvt_f32_f16_sdwa v119, v142 dst_sel:DWORD dst_unused:UNUSED_PAD src0_sel:WORD_1
	v_lshl_add_u64 v[132:133], s[16:17], 0, v[132:133]
	v_perm_b32 v128, v129, v128, s1
	v_lshl_add_u64 v[158:159], v[132:133], 0, v[184:185]
	v_perm_b32 v126, v128, v126, s51
	v_rcp_f32_e32 v76, v76
	v_rcp_f32_e32 v77, v77
	v_cvt_f32_f16_e32 v120, v143
	v_cvt_f32_f16_sdwa v121, v143 dst_sel:DWORD dst_unused:UNUSED_PAD src0_sel:WORD_1
	global_store_dwordx4 v[158:159], v[114:117], off
	global_store_dwordx2 v[160:161], v[126:127], off
	s_waitcnt vmcnt(6)
	v_lshlrev_b32_e32 v126, 16, v138
	v_and_b32_e32 v127, 0xffff0000, v138
	v_rcp_f32_e32 v78, v78
	v_rcp_f32_e32 v79, v79
	v_pk_fma_f32 v[74:75], v[74:75], v[126:127], v[118:119]
	v_cvt_f32_f16_e32 v118, v144
	v_cvt_f32_f16_sdwa v119, v144 dst_sel:DWORD dst_unused:UNUSED_PAD src0_sel:WORD_1
	v_lshlrev_b32_e32 v128, 16, v139
	v_and_b32_e32 v129, 0xffff0000, v139
	v_rcp_f32_e32 v80, v80
	v_rcp_f32_e32 v81, v81
	v_pk_fma_f32 v[76:77], v[76:77], v[128:129], v[120:121]
	v_cvt_f32_f16_e32 v120, v145
	v_cvt_f32_f16_sdwa v121, v145 dst_sel:DWORD dst_unused:UNUSED_PAD src0_sel:WORD_1
	v_lshlrev_b32_e32 v126, 16, v140
	v_and_b32_e32 v127, 0xffff0000, v140
	v_pk_fma_f32 v[78:79], v[78:79], v[126:127], v[118:119]
	v_cvt_pk_f16_f32 v118, v74, v75
	v_cvt_pk_f16_f32 v119, v76, v77
	v_pk_fma_f32 v[74:75], v[194:195], v[74:75], s[42:43] op_sel_hi:[0,1,0]
	v_pk_fma_f32 v[76:77], v[194:195], v[76:77], s[42:43] op_sel_hi:[0,1,0]
	v_lshlrev_b32_e32 v128, 16, v141
	v_and_b32_e32 v129, 0xffff0000, v141
	v_med3_f32 v74, v74, s93, v221
	v_med3_f32 v75, v75, s93, v221
	v_med3_f32 v76, v76, s93, v221
	v_med3_f32 v77, v77, s93, v221
	v_pk_fma_f32 v[80:81], v[80:81], v[128:129], v[120:121]
	v_perm_b32 v76, v77, v76, s1
	v_perm_b32 v74, v75, v74, s1
	v_cvt_pk_f16_f32 v120, v78, v79
	v_perm_b32 v74, v76, v74, s51
	v_pk_fma_f32 v[76:77], v[194:195], v[78:79], s[42:43] op_sel_hi:[0,1,0]
	v_pk_fma_f32 v[78:79], v[194:195], v[80:81], s[42:43] op_sel_hi:[0,1,0]
	v_med3_f32 v75, v76, s93, v221
	v_med3_f32 v76, v77, s93, v221
	v_med3_f32 v77, v78, s93, v221
	v_med3_f32 v78, v79, s93, v221
	v_lshlrev_b64 v[126:127], 12, v[188:189]
	v_perm_b32 v77, v78, v77, s1
	v_perm_b32 v75, v76, v75, s1
	v_lshl_add_u64 v[126:127], s[16:17], 0, v[126:127]
	v_perm_b32 v75, v77, v75, s51
	v_lshl_add_u64 v[76:77], s[20:21], 0, v[208:209]
	v_cvt_pk_f16_f32 v121, v80, v81
	v_lshl_add_u64 v[214:215], v[126:127], 0, v[184:185]
	v_lshl_add_u64 v[152:153], v[76:77], 0, v[182:183]
	v_or_b32_e32 v150, 0x80, v182
	v_mov_b32_e32 v151, v183
	global_store_dwordx4 v[214:215], v[118:121], off
	global_store_dwordx2 v[152:153], v[74:75], off
	v_lshl_add_u64 v[74:75], v[202:203], 0, v[150:151]
	v_lshlrev_b64 v[74:75], 1, v[74:75]
	v_lshl_add_u64 v[76:77], s[14:15], 0, v[74:75]
	global_load_dwordx4 v[232:235], v[76:77], off
	v_lshl_add_u64 v[74:75], s[10:11], 0, v[74:75]
	global_load_dwordx4 v[236:239], v[242:243], off offset:1024
	v_lshl_add_u64 v[126:127], v[204:205], 0, v[150:151]
	v_lshlrev_b64 v[126:127], 1, v[126:127]
	v_lshl_add_u64 v[128:129], s[14:15], 0, v[126:127]
	ds_read_b128 v[78:81], v231 offset:4608
	ds_read_b128 v[74:77], v231 offset:4624
	global_load_dwordx4 v[146:149], v[128:129], off
	v_lshl_add_u64 v[126:127], s[10:11], 0, v[126:127]
	global_load_dwordx4 v[142:145], v[242:243], off offset:3072
	v_cvt_f32_i32_e32 v110, v110
	v_cvt_f32_i32_e32 v106, v106
	v_lshl_add_u64 v[126:127], v[206:207], 0, v[150:151]
	v_lshlrev_b64 v[126:127], 1, v[126:127]
	v_mul_f32_e32 v110, v230, v110
	v_mul_f32_e32 v106, v230, v106
	v_cvt_f32_i32_e32 v111, v111
	v_cvt_f32_i32_e32 v107, v107
	v_lshl_add_u64 v[128:129], s[14:15], 0, v[126:127]
	s_waitcnt lgkmcnt(1)
	v_mul_f32_e32 v110, v110, v78
	s_waitcnt lgkmcnt(0)
	v_mul_f32_e32 v106, v106, v74
	global_load_dwordx4 v[138:141], v[128:129], off
	v_mul_f32_e32 v110, 0xbfb8aa3b, v110
	v_mul_f32_e32 v106, 0xbfb8aa3b, v106
	v_exp_f32_e32 v110, v110
	v_exp_f32_e32 v168, v106
	v_lshl_add_u64 v[126:127], s[10:11], 0, v[126:127]
	v_mul_f32_e32 v111, v230, v111
	v_mul_f32_e32 v107, v230, v107
	v_cvt_f32_i32_e32 v112, v112
	v_cvt_f32_i32_e32 v108, v108
	global_load_dwordx4 v[134:137], v[244:245], off offset:1024
	v_mul_f32_e32 v111, v111, v79
	v_mul_f32_e32 v107, v107, v75
	v_mul_f32_e32 v111, 0xbfb8aa3b, v111
	v_mul_f32_e32 v107, 0xbfb8aa3b, v107
	v_add_f32_e32 v106, 1.0, v110
	v_add_f32_e32 v110, 1.0, v168
	v_exp_f32_e32 v111, v111
	v_exp_f32_e32 v168, v107
	v_mul_f32_e32 v112, v230, v112
	v_mul_f32_e32 v108, v230, v108
	v_cvt_f32_i32_e32 v113, v113
	v_cvt_f32_i32_e32 v109, v109
	v_mul_f32_e32 v112, v112, v80
	v_mul_f32_e32 v108, v108, v76
	v_mul_f32_e32 v112, 0xbfb8aa3b, v112
	v_mul_f32_e32 v108, 0xbfb8aa3b, v108
	v_add_f32_e32 v107, 1.0, v111
	v_add_f32_e32 v111, 1.0, v168
	v_exp_f32_e32 v112, v112
	v_exp_f32_e32 v168, v108
	v_mul_f32_e32 v113, v230, v113
	v_mul_f32_e32 v109, v230, v109
	v_mul_f32_e32 v113, v113, v81
	v_mul_f32_e32 v109, v109, v77
	v_mul_f32_e32 v113, 0xbfb8aa3b, v113
	v_mul_f32_e32 v109, 0xbfb8aa3b, v109
	v_add_f32_e32 v108, 1.0, v112
	v_add_f32_e32 v112, 1.0, v168
	v_exp_f32_e32 v113, v113
	v_exp_f32_e32 v168, v109
	v_rcp_f32_e32 v106, v106
	v_rcp_f32_e32 v107, v107
	v_add_f32_e32 v109, 1.0, v113
	v_add_f32_e32 v113, 1.0, v168
	v_rcp_f32_e32 v108, v108
	v_rcp_f32_e32 v109, v109
	v_rcp_f32_e32 v110, v110
	v_rcp_f32_e32 v111, v111
	v_rcp_f32_e32 v112, v112
	v_rcp_f32_e32 v113, v113
	v_lshl_add_u64 v[126:127], v[208:209], 0, v[150:151]
	v_lshlrev_b64 v[126:127], 1, v[126:127]
	v_lshl_add_u64 v[128:129], s[14:15], 0, v[126:127]
	v_add_f32_e32 v240, 0, v130
	global_load_dwordx4 v[130:133], v[128:129], off
	v_lshl_add_u64 v[126:127], s[10:11], 0, v[126:127]
	global_load_dwordx4 v[126:129], v[244:245], off offset:3072
	v_cvt_f32_i32_e32 v102, v102
	s_waitcnt vmcnt(7)
	v_cvt_f32_f16_e32 v168, v232
	v_cvt_f32_f16_sdwa v169, v232 dst_sel:DWORD dst_unused:UNUSED_PAD src0_sel:WORD_1
	v_cvt_f32_f16_e32 v170, v233
	v_cvt_f32_f16_sdwa v171, v233 dst_sel:DWORD dst_unused:UNUSED_PAD src0_sel:WORD_1
	s_waitcnt vmcnt(6)
	v_lshlrev_b32_e32 v202, 16, v236
	v_and_b32_e32 v203, 0xffff0000, v236
	v_pk_fma_f32 v[168:169], v[106:107], v[202:203], v[168:169]
	v_cvt_f32_f16_e32 v106, v234
	v_cvt_f32_f16_sdwa v107, v234 dst_sel:DWORD dst_unused:UNUSED_PAD src0_sel:WORD_1
	v_lshlrev_b32_e32 v204, 16, v237
	v_and_b32_e32 v205, 0xffff0000, v237
	v_pk_fma_f32 v[170:171], v[108:109], v[204:205], v[170:171]
	v_cvt_f32_f16_e32 v108, v235
	v_cvt_f32_f16_sdwa v109, v235 dst_sel:DWORD dst_unused:UNUSED_PAD src0_sel:WORD_1
	v_lshlrev_b32_e32 v202, 16, v238
	v_and_b32_e32 v203, 0xffff0000, v238
	v_pk_fma_f32 v[110:111], v[110:111], v[202:203], v[106:107]
	v_cvt_pk_f16_f32 v106, v168, v169
	v_mov_b32_e32 v202, 0
	v_lshlrev_b32_e32 v204, 16, v239
	v_and_b32_e32 v205, 0xffff0000, v239
	v_cvt_pk_f16_f32 v107, v170, v171
	v_dot2c_f32_f16_e32 v202, v106, v106
	v_pk_fma_f32 v[112:113], v[112:113], v[204:205], v[108:109]
	v_cvt_pk_f16_f32 v108, v110, v111
	v_dot2c_f32_f16_e32 v202, v107, v107
	v_cvt_pk_f16_f32 v109, v112, v113
	v_dot2c_f32_f16_e32 v202, v108, v108
	global_store_dwordx4 v[210:211], v[106:109], off offset:256
	v_dot2c_f32_f16_e32 v202, v109, v109
	v_cvt_f32_i32_e32 v98, v98
	v_pk_fma_f32 v[106:107], v[200:201], v[168:169], s[42:43] op_sel_hi:[0,1,0]
	v_pk_fma_f32 v[108:109], v[200:201], v[170:171], s[42:43] op_sel_hi:[0,1,0]
	v_med3_f32 v106, v106, s93, v221
	v_med3_f32 v107, v107, s93, v221
	v_med3_f32 v108, v108, s93, v221
	v_med3_f32 v109, v109, s93, v221
	v_perm_b32 v108, v109, v108, s1
	v_perm_b32 v106, v107, v106, s1
	v_perm_b32 v106, v108, v106, s51
	v_pk_fma_f32 v[108:109], v[200:201], v[110:111], s[42:43] op_sel_hi:[0,1,0]
	v_pk_fma_f32 v[110:111], v[200:201], v[112:113], s[42:43] op_sel_hi:[0,1,0]
	v_med3_f32 v107, v108, s93, v221
	v_med3_f32 v108, v109, s93, v221
	v_med3_f32 v109, v110, s93, v221
	v_med3_f32 v110, v111, s93, v221
	v_mul_f32_e32 v102, v229, v102
	v_mul_f32_e32 v98, v229, v98
	v_cvt_f32_i32_e32 v103, v103
	v_cvt_f32_i32_e32 v99, v99
	v_perm_b32 v109, v110, v109, s1
	v_perm_b32 v107, v108, v107, s1
	v_mul_f32_e32 v102, v102, v78
	v_mul_f32_e32 v98, v98, v74
	v_perm_b32 v107, v109, v107, s51
	v_mul_f32_e32 v102, 0xbfb8aa3b, v102
	v_mul_f32_e32 v98, 0xbfb8aa3b, v98
	global_store_dwordx2 v[212:213], v[106:107], off offset:128
	v_exp_f32_e32 v102, v102
	v_exp_f32_e32 v106, v98
	v_mul_f32_e32 v103, v229, v103
	v_mul_f32_e32 v99, v229, v99
	v_cvt_f32_i32_e32 v104, v104
	v_cvt_f32_i32_e32 v100, v100
	v_mul_f32_e32 v103, v103, v79
	v_mul_f32_e32 v99, v99, v75
	v_mul_f32_e32 v103, 0xbfb8aa3b, v103
	v_mul_f32_e32 v99, 0xbfb8aa3b, v99
	v_add_f32_e32 v98, 1.0, v102
	v_add_f32_e32 v102, 1.0, v106
	v_exp_f32_e32 v103, v103
	v_exp_f32_e32 v106, v99
	v_cvt_f32_i32_e32 v105, v105
	v_mul_f32_e32 v104, v229, v104
	v_mul_f32_e32 v100, v229, v100
	v_cvt_f32_i32_e32 v101, v101
	v_mul_f32_e32 v104, v104, v80
	v_mul_f32_e32 v100, v100, v76
	v_mul_f32_e32 v104, 0xbfb8aa3b, v104
	v_mul_f32_e32 v100, 0xbfb8aa3b, v100
	v_add_f32_e32 v99, 1.0, v103
	v_add_f32_e32 v103, 1.0, v106
	v_exp_f32_e32 v104, v104
	v_exp_f32_e32 v106, v100
	v_mul_f32_e32 v105, v229, v105
	v_mul_f32_e32 v105, v105, v81
	v_mul_f32_e32 v101, v229, v101
	v_mul_f32_e32 v105, 0xbfb8aa3b, v105
	v_mul_f32_e32 v101, v101, v77
	v_exp_f32_e32 v105, v105
	v_mul_f32_e32 v101, 0xbfb8aa3b, v101
	v_add_f32_e32 v100, 1.0, v104
	v_add_f32_e32 v104, 1.0, v106
	v_exp_f32_e32 v106, v101
	v_add_f32_e32 v101, 1.0, v105
	v_rcp_f32_e32 v98, v98
	v_rcp_f32_e32 v99, v99
	v_rcp_f32_e32 v100, v100
	v_rcp_f32_e32 v101, v101
	v_add_f32_e32 v105, 1.0, v106
	s_waitcnt vmcnt(7)
	v_cvt_f32_f16_e32 v106, v146
	v_cvt_f32_f16_sdwa v107, v146 dst_sel:DWORD dst_unused:UNUSED_PAD src0_sel:WORD_1
	v_cvt_f32_f16_e32 v108, v147
	v_cvt_f32_f16_sdwa v109, v147 dst_sel:DWORD dst_unused:UNUSED_PAD src0_sel:WORD_1
	s_waitcnt vmcnt(6)
	v_lshlrev_b32_e32 v110, 16, v142
	v_and_b32_e32 v111, 0xffff0000, v142
	v_lshlrev_b32_e32 v112, 16, v143
	v_and_b32_e32 v113, 0xffff0000, v143
	v_rcp_f32_e32 v102, v102
	v_rcp_f32_e32 v103, v103
	v_rcp_f32_e32 v104, v104
	v_rcp_f32_e32 v105, v105
	v_pk_fma_f32 v[108:109], v[100:101], v[112:113], v[108:109]
	v_pk_fma_f32 v[106:107], v[98:99], v[110:111], v[106:107]
	v_cvt_f32_f16_e32 v98, v148
	v_cvt_f32_f16_sdwa v99, v148 dst_sel:DWORD dst_unused:UNUSED_PAD src0_sel:WORD_1
	v_cvt_f32_f16_e32 v100, v149
	v_cvt_f32_f16_sdwa v101, v149 dst_sel:DWORD dst_unused:UNUSED_PAD src0_sel:WORD_1
	v_cvt_f32_i32_e32 v94, v94
	v_cvt_f32_i32_e32 v90, v90
	v_lshlrev_b32_e32 v110, 16, v144
	v_and_b32_e32 v111, 0xffff0000, v144
	v_lshlrev_b32_e32 v112, 16, v145
	v_and_b32_e32 v113, 0xffff0000, v145
	v_pk_fma_f32 v[104:105], v[104:105], v[112:113], v[100:101]
	v_pk_fma_f32 v[102:103], v[102:103], v[110:111], v[98:99]
	v_cvt_pk_f16_f32 v101, v104, v105
	v_cvt_pk_f16_f32 v100, v102, v103
	v_pk_fma_f32 v[102:103], v[198:199], v[102:103], s[42:43] op_sel_hi:[0,1,0]
	v_pk_fma_f32 v[104:105], v[198:199], v[104:105], s[42:43] op_sel_hi:[0,1,0]
	v_mul_f32_e32 v94, v228, v94
	v_mul_f32_e32 v90, v228, v90
	v_cvt_f32_i32_e32 v95, v95
	v_cvt_f32_i32_e32 v91, v91
	v_cvt_pk_f16_f32 v98, v106, v107
	v_pk_fma_f32 v[106:107], v[198:199], v[106:107], s[42:43] op_sel_hi:[0,1,0]
	v_med3_f32 v102, v102, s93, v221
	v_med3_f32 v103, v103, s93, v221
	v_med3_f32 v104, v104, s93, v221
	v_med3_f32 v105, v105, s93, v221
	v_mul_f32_e32 v94, v94, v78
	v_mul_f32_e32 v90, v90, v74
	v_med3_f32 v106, v106, s93, v221
	v_med3_f32 v107, v107, s93, v221
	v_perm_b32 v104, v105, v104, s1
	v_perm_b32 v102, v103, v102, s1
	v_mul_f32_e32 v94, 0xbfb8aa3b, v94
	v_mul_f32_e32 v90, 0xbfb8aa3b, v90
	v_perm_b32 v106, v107, v106, s1
	v_perm_b32 v107, v104, v102, s51
	v_exp_f32_e32 v94, v94
	v_exp_f32_e32 v102, v90
	v_mul_f32_e32 v95, v228, v95
	v_mul_f32_e32 v91, v228, v91
	v_cvt_f32_i32_e32 v96, v96
	v_cvt_f32_i32_e32 v92, v92
	v_mul_f32_e32 v95, v95, v79
	v_mul_f32_e32 v91, v91, v75
	v_mul_f32_e32 v95, 0xbfb8aa3b, v95
	v_mul_f32_e32 v91, 0xbfb8aa3b, v91
	v_add_f32_e32 v90, 1.0, v94
	v_add_f32_e32 v94, 1.0, v102
	v_exp_f32_e32 v95, v95
	v_exp_f32_e32 v102, v91
	v_cvt_f32_i32_e32 v97, v97
	v_mul_f32_e32 v96, v228, v96
	v_mul_f32_e32 v92, v228, v92
	v_cvt_f32_i32_e32 v93, v93
	v_mul_f32_e32 v96, v96, v80
	v_mul_f32_e32 v92, v92, v76
	v_mul_f32_e32 v96, 0xbfb8aa3b, v96
	v_mul_f32_e32 v92, 0xbfb8aa3b, v92
	v_add_f32_e32 v91, 1.0, v95
	v_add_f32_e32 v95, 1.0, v102
	v_exp_f32_e32 v96, v96
	v_exp_f32_e32 v102, v92
	v_mul_f32_e32 v97, v228, v97
	v_mul_f32_e32 v97, v97, v81
	v_mul_f32_e32 v93, v228, v93
	v_mul_f32_e32 v97, 0xbfb8aa3b, v97
	v_mul_f32_e32 v93, v93, v77
	v_exp_f32_e32 v97, v97
	v_mul_f32_e32 v93, 0xbfb8aa3b, v93
	v_add_f32_e32 v92, 1.0, v96
	v_add_f32_e32 v96, 1.0, v102
	v_exp_f32_e32 v102, v93
	v_cvt_pk_f16_f32 v99, v108, v109
	v_pk_fma_f32 v[108:109], v[198:199], v[108:109], s[42:43] op_sel_hi:[0,1,0]
	v_add_f32_e32 v93, 1.0, v97
	v_med3_f32 v108, v108, s93, v221
	v_med3_f32 v109, v109, s93, v221
	v_rcp_f32_e32 v90, v90
	v_rcp_f32_e32 v91, v91
	v_rcp_f32_e32 v92, v92
	v_rcp_f32_e32 v93, v93
	v_add_f32_e32 v97, 1.0, v102
	s_waitcnt vmcnt(5)
	v_cvt_f32_f16_e32 v102, v138
	v_cvt_f32_f16_sdwa v103, v138 dst_sel:DWORD dst_unused:UNUSED_PAD src0_sel:WORD_1
	v_cvt_f32_f16_e32 v104, v139
	v_cvt_f32_f16_sdwa v105, v139 dst_sel:DWORD dst_unused:UNUSED_PAD src0_sel:WORD_1
	v_perm_b32 v108, v109, v108, s1
	v_perm_b32 v106, v108, v106, s51
	global_store_dwordx4 v[154:155], v[98:101], off offset:256
	global_store_dwordx2 v[156:157], v[106:107], off offset:128
	s_waitcnt vmcnt(6)
	v_lshlrev_b32_e32 v106, 16, v134
	v_and_b32_e32 v107, 0xffff0000, v134
	v_lshlrev_b32_e32 v108, 16, v135
	v_and_b32_e32 v109, 0xffff0000, v135
	v_rcp_f32_e32 v94, v94
	v_rcp_f32_e32 v95, v95
	v_rcp_f32_e32 v96, v96
	v_rcp_f32_e32 v97, v97
	v_pk_fma_f32 v[104:105], v[92:93], v[108:109], v[104:105]
	v_pk_fma_f32 v[102:103], v[90:91], v[106:107], v[102:103]
	v_cvt_f32_f16_e32 v90, v140
	v_cvt_f32_f16_sdwa v91, v140 dst_sel:DWORD dst_unused:UNUSED_PAD src0_sel:WORD_1
	v_cvt_f32_f16_e32 v92, v141
	v_cvt_f32_f16_sdwa v93, v141 dst_sel:DWORD dst_unused:UNUSED_PAD src0_sel:WORD_1
	v_cvt_f32_i32_e32 v86, v86
	v_cvt_f32_i32_e32 v82, v82
	v_lshlrev_b32_e32 v106, 16, v136
	v_and_b32_e32 v107, 0xffff0000, v136
	v_lshlrev_b32_e32 v108, 16, v137
	v_and_b32_e32 v109, 0xffff0000, v137
	v_pk_fma_f32 v[96:97], v[96:97], v[108:109], v[92:93]
	v_pk_fma_f32 v[94:95], v[94:95], v[106:107], v[90:91]
	v_cvt_pk_f16_f32 v93, v96, v97
	v_cvt_pk_f16_f32 v92, v94, v95
	v_pk_fma_f32 v[94:95], v[196:197], v[94:95], s[42:43] op_sel_hi:[0,1,0]
	v_pk_fma_f32 v[96:97], v[196:197], v[96:97], s[42:43] op_sel_hi:[0,1,0]
	v_mul_f32_e32 v86, v227, v86
	v_mul_f32_e32 v82, v227, v82
	v_cvt_f32_i32_e32 v87, v87
	v_cvt_f32_i32_e32 v83, v83
	v_cvt_pk_f16_f32 v90, v102, v103
	v_pk_fma_f32 v[102:103], v[196:197], v[102:103], s[42:43] op_sel_hi:[0,1,0]
	v_med3_f32 v94, v94, s93, v221
	v_med3_f32 v95, v95, s93, v221
	v_med3_f32 v96, v96, s93, v221
	v_med3_f32 v97, v97, s93, v221
	v_mul_f32_e32 v86, v86, v78
	v_mul_f32_e32 v82, v82, v74
	v_med3_f32 v102, v102, s93, v221
	v_med3_f32 v103, v103, s93, v221
	v_perm_b32 v96, v97, v96, s1
	v_perm_b32 v94, v95, v94, s1
	v_mul_f32_e32 v86, 0xbfb8aa3b, v86
	v_mul_f32_e32 v82, 0xbfb8aa3b, v82
	v_perm_b32 v102, v103, v102, s1
	v_perm_b32 v103, v96, v94, s51
	v_exp_f32_e32 v86, v86
	v_exp_f32_e32 v94, v82
	v_mul_f32_e32 v87, v227, v87
	v_mul_f32_e32 v83, v227, v83
	v_cvt_f32_i32_e32 v88, v88
	v_cvt_f32_i32_e32 v84, v84
	v_mul_f32_e32 v87, v87, v79
	v_mul_f32_e32 v83, v83, v75
	v_mul_f32_e32 v87, 0xbfb8aa3b, v87
	v_mul_f32_e32 v83, 0xbfb8aa3b, v83
	v_add_f32_e32 v82, 1.0, v86
	v_add_f32_e32 v86, 1.0, v94
	v_exp_f32_e32 v87, v87
	v_exp_f32_e32 v94, v83
	v_mul_f32_e32 v88, v227, v88
	v_mul_f32_e32 v84, v227, v84
	v_cvt_f32_i32_e32 v89, v89
	v_cvt_f32_i32_e32 v85, v85
	v_mul_f32_e32 v88, v88, v80
	v_mul_f32_e32 v84, v84, v76
	v_mul_f32_e32 v88, 0xbfb8aa3b, v88
	v_mul_f32_e32 v84, 0xbfb8aa3b, v84
	v_add_f32_e32 v83, 1.0, v87
	v_add_f32_e32 v87, 1.0, v94
	v_exp_f32_e32 v88, v88
	v_exp_f32_e32 v94, v84
	v_mul_f32_e32 v89, v227, v89
	v_mul_f32_e32 v85, v227, v85
	v_mul_f32_e32 v89, v89, v81
	v_mul_f32_e32 v85, v85, v77
	v_mul_f32_e32 v89, 0xbfb8aa3b, v89
	v_mul_f32_e32 v85, 0xbfb8aa3b, v85
	v_add_f32_e32 v84, 1.0, v88
	v_add_f32_e32 v88, 1.0, v94
	v_exp_f32_e32 v89, v89
	v_exp_f32_e32 v94, v85
	v_cvt_pk_f16_f32 v91, v104, v105
	v_pk_fma_f32 v[104:105], v[196:197], v[104:105], s[42:43] op_sel_hi:[0,1,0]
	v_med3_f32 v104, v104, s93, v221
	v_med3_f32 v105, v105, s93, v221
	v_rcp_f32_e32 v82, v82
	v_rcp_f32_e32 v83, v83
	v_add_f32_e32 v85, 1.0, v89
	v_add_f32_e32 v89, 1.0, v94
	s_waitcnt vmcnt(5)
	v_cvt_f32_f16_e32 v94, v130
	v_cvt_f32_f16_sdwa v95, v130 dst_sel:DWORD dst_unused:UNUSED_PAD src0_sel:WORD_1
	v_perm_b32 v104, v105, v104, s1
	v_perm_b32 v102, v104, v102, s51
	global_store_dwordx4 v[158:159], v[90:93], off offset:256
	global_store_dwordx2 v[160:161], v[102:103], off offset:128
	s_waitcnt vmcnt(6)
	v_lshlrev_b32_e32 v102, 16, v126
	v_and_b32_e32 v103, 0xffff0000, v126
	v_rcp_f32_e32 v86, v86
	v_rcp_f32_e32 v87, v87
	v_pk_fma_f32 v[94:95], v[82:83], v[102:103], v[94:95]
	v_cvt_f32_f16_e32 v82, v132
	v_cvt_f32_f16_sdwa v83, v132 dst_sel:DWORD dst_unused:UNUSED_PAD src0_sel:WORD_1
	v_rcp_f32_e32 v84, v84
	v_rcp_f32_e32 v85, v85
	v_cvt_f32_f16_e32 v96, v131
	v_cvt_f32_f16_sdwa v97, v131 dst_sel:DWORD dst_unused:UNUSED_PAD src0_sel:WORD_1
	v_lshlrev_b32_e32 v102, 16, v128
	v_and_b32_e32 v103, 0xffff0000, v128
	v_pk_fma_f32 v[86:87], v[86:87], v[102:103], v[82:83]
	v_cvt_pk_f16_f32 v82, v94, v95
	v_pk_fma_f32 v[94:95], v[194:195], v[94:95], s[42:43] op_sel_hi:[0,1,0]
	v_add_f32_e32 v202, v240, v202
	v_lshlrev_b32_e32 v104, 16, v127
	v_and_b32_e32 v105, 0xffff0000, v127
	v_med3_f32 v94, v94, s93, v221
	v_med3_f32 v95, v95, s93, v221
	v_rcp_f32_e32 v88, v88
	v_rcp_f32_e32 v89, v89
	v_pk_fma_f32 v[96:97], v[84:85], v[104:105], v[96:97]
	v_cvt_f32_f16_e32 v84, v133
	v_cvt_f32_f16_sdwa v85, v133 dst_sel:DWORD dst_unused:UNUSED_PAD src0_sel:WORD_1
	v_perm_b32 v94, v95, v94, s1
	ds_bpermute_b32 v95, v223, v202
	v_cvt_pk_f16_f32 v83, v96, v97
	v_pk_fma_f32 v[96:97], v[194:195], v[96:97], s[42:43] op_sel_hi:[0,1,0]
	v_lshlrev_b32_e32 v104, 16, v129
	v_and_b32_e32 v105, 0xffff0000, v129
	v_med3_f32 v96, v96, s93, v221
	v_med3_f32 v97, v97, s93, v221
	v_pk_fma_f32 v[88:89], v[88:89], v[104:105], v[84:85]
	v_cvt_pk_f16_f32 v84, v86, v87
	v_perm_b32 v96, v97, v96, s1
	v_pk_fma_f32 v[86:87], v[194:195], v[86:87], s[42:43] op_sel_hi:[0,1,0]
	v_perm_b32 v94, v96, v94, s51
	v_med3_f32 v96, v86, s93, v221
	s_waitcnt lgkmcnt(0)
	v_add_f32_e32 v86, v202, v95
	v_med3_f32 v97, v87, s93, v221
	ds_bpermute_b32 v87, v224, v86
	v_cvt_pk_f16_f32 v85, v88, v89
	v_pk_fma_f32 v[88:89], v[194:195], v[88:89], s[42:43] op_sel_hi:[0,1,0]
	v_med3_f32 v88, v88, s93, v221
	v_med3_f32 v89, v89, s93, v221
	v_perm_b32 v88, v89, v88, s1
	v_perm_b32 v89, v97, v96, s1
	v_perm_b32 v95, v88, v89, s51
	global_store_dwordx4 v[214:215], v[82:85], off offset:256
	global_store_dwordx2 v[152:153], v[94:95], off offset:128
	s_and_saveexec_b64 s[26:27], s[4:5]
	s_cbranch_execz .LBB0_1620
	s_waitcnt lgkmcnt(0)
	v_add_f32_e32 v86, v86, v87
	v_fma_f32 v86, v86, s33, 0.5
	v_trunc_f32_e32 v86, v86
	v_mul_f32_e32 v87, 0x2f800000, v86
	v_floor_f32_e32 v87, v87
	v_fmac_f32_e32 v86, 0xcf800000, v87
	v_cvt_u32_f32_e32 v86, v86
	v_cvt_u32_f32_e32 v87, v87
	v_lshl_add_u64 v[88:89], v[186:187], 3, s[18:19]
	global_atomic_add_x2 v[88:89], v[86:87], off

.LBB0_1626:
	s_or_b64 exec, exec, s[26:27]
	s_waitcnt lgkmcnt(0)
	ds_read2_b64 v[82:85], v225 offset0:128 offset1:144
	ds_read2_b64 v[86:89], v226 offset0:128 offset1:144
	ds_read2_b64 v[90:93], v225 offset0:160 offset1:176
	ds_read2_b64 v[94:97], v226 offset0:160 offset1:176
	v_add_u32_e32 v112, 0x80, v186
	v_ashrrev_i32_e32 v113, 31, v112
	s_waitcnt lgkmcnt(3)
	v_cvt_f32_u32_e32 v83, v83
	s_waitcnt lgkmcnt(2)
	v_cvt_f32_u32_e32 v87, v87
	v_cvt_f32_u32_e32 v86, v86
	v_cvt_f32_u32_e32 v82, v82
	v_cvt_f32_u32_e32 v85, v85
	v_cvt_f32_u32_e32 v84, v84
	v_fmac_f32_e32 v86, 0x4f800000, v87
	v_fmac_f32_e32 v82, 0x4f800000, v83
	v_fmamk_f32 v83, v86, 0x30000000, v1
	v_rsq_f32_e32 v86, v83
	v_cvt_f32_u32_e32 v88, v88
	v_fmamk_f32 v82, v82, 0x30000000, v1
	v_fmac_f32_e32 v84, 0x4f800000, v85
	v_mul_f32_e32 v83, v83, v86
	v_cvt_f32_u32_e32 v86, v89
	v_rsq_f32_e32 v82, v82
	v_fmamk_f32 v84, v84, 0x30000000, v1
	v_rsq_f32_e32 v84, v84
	v_fmac_f32_e32 v88, 0x4f800000, v86
	v_fmamk_f32 v85, v88, 0x30000000, v1
	v_rsq_f32_e32 v86, v85
	v_mul_f32_e32 v87, 0x3d214285, v82
	v_mul_f32_e32 v121, v87, v83
	v_mul_f32_e32 v120, 0x41cb3333, v82
	v_mul_f32_e32 v82, 0x3d214285, v84
	v_mul_f32_e32 v83, v85, v86
	v_mul_f32_e32 v119, v82, v83
	s_waitcnt lgkmcnt(1)
	v_cvt_f32_u32_e32 v82, v91
	v_cvt_f32_u32_e32 v83, v90
	v_mul_f32_e32 v118, 0x41cb3333, v84
	s_waitcnt lgkmcnt(0)
	v_cvt_f32_u32_e32 v84, v95
	v_cvt_f32_u32_e32 v85, v94
	v_fmac_f32_e32 v83, 0x4f800000, v82
	v_fmamk_f32 v82, v83, 0x30000000, v1
	v_cvt_f32_u32_e32 v86, v93
	v_fmac_f32_e32 v85, 0x4f800000, v84
	v_fmamk_f32 v83, v85, 0x30000000, v1
	v_rsq_f32_e32 v84, v83
	v_cvt_f32_u32_e32 v87, v92
	v_cvt_f32_u32_e32 v88, v96
	v_rsq_f32_e32 v82, v82
	v_mul_f32_e32 v83, v83, v84
	v_cvt_f32_u32_e32 v84, v97
	v_fmac_f32_e32 v87, 0x4f800000, v86
	v_fmamk_f32 v86, v87, 0x30000000, v1
	v_rsq_f32_e32 v86, v86
	v_fmac_f32_e32 v88, 0x4f800000, v84
	v_fmamk_f32 v84, v88, 0x30000000, v1
	v_rsq_f32_e32 v87, v84
	v_mul_f32_e32 v85, 0x3d214285, v82
	v_mul_f32_e32 v117, v85, v83
	v_mul_f32_e32 v116, 0x41cb3333, v82
	v_mul_f32_e32 v82, 0x3d214285, v86
	v_mul_f32_e32 v83, v84, v87
	v_lshlrev_b64 v[122:123], 11, v[112:113]
	v_mul_f32_e32 v115, v82, v83
	v_lshl_add_u64 v[82:83], v[122:123], 0, v[182:183]
	v_lshlrev_b64 v[82:83], 1, v[82:83]
	v_lshl_add_u64 v[84:85], s[14:15], 0, v[82:83]
	global_load_dwordx4 v[130:133], v[84:85], off
	v_lshl_add_u64 v[82:83], s[10:11], 0, v[82:83]
	global_load_dwordx4 v[134:137], v[246:247], off
	v_add_u32_e32 v110, 0x90, v186
	v_ashrrev_i32_e32 v111, 31, v110
	v_lshlrev_b64 v[124:125], 11, v[110:111]
	v_lshl_add_u64 v[82:83], v[124:125], 0, v[182:183]
	v_lshlrev_b64 v[82:83], 1, v[82:83]
	v_lshl_add_u64 v[84:85], s[14:15], 0, v[82:83]
	global_load_dwordx4 v[102:105], v[84:85], off
	v_lshl_add_u64 v[82:83], s[10:11], 0, v[82:83]
	global_load_dwordx4 v[98:101], v[246:247], off offset:2048
	v_cvt_f32_i32_e32 v62, v62
	v_cvt_f32_i32_e32 v58, v58
	v_add_u32_e32 v108, 0xa0, v186
	v_ashrrev_i32_e32 v109, 31, v108
	v_lshlrev_b64 v[126:127], 11, v[108:109]
	v_lshl_add_u64 v[82:83], v[126:127], 0, v[182:183]
	v_mul_f32_e32 v62, v121, v62
	v_mul_f32_e32 v58, v121, v58
	v_cvt_f32_i32_e32 v63, v63
	v_cvt_f32_i32_e32 v59, v59
	v_lshlrev_b64 v[82:83], 1, v[82:83]
	v_mul_f32_e32 v62, v70, v62
	v_mul_f32_e32 v58, v66, v58
	v_lshl_add_u64 v[84:85], s[14:15], 0, v[82:83]
	v_mul_f32_e32 v62, 0xbfb8aa3b, v62
	v_mul_f32_e32 v58, 0xbfb8aa3b, v58
	global_load_dwordx4 v[94:97], v[84:85], off
	v_exp_f32_e32 v62, v62
	v_exp_f32_e32 v138, v58
	v_mul_f32_e32 v63, v121, v63
	v_mul_f32_e32 v59, v121, v59
	v_cvt_f32_i32_e32 v64, v64
	v_cvt_f32_i32_e32 v60, v60
	v_lshl_add_u64 v[82:83], s[10:11], 0, v[82:83]
	v_mul_f32_e32 v63, v71, v63
	v_mul_f32_e32 v59, v67, v59
	global_load_dwordx4 v[90:93], v[248:249], off
	v_mul_f32_e32 v63, 0xbfb8aa3b, v63
	v_mul_f32_e32 v59, 0xbfb8aa3b, v59
	v_add_f32_e32 v58, 1.0, v62
	v_add_f32_e32 v62, 1.0, v138
	v_exp_f32_e32 v63, v63
	v_exp_f32_e32 v138, v59
	v_cvt_f32_i32_e32 v65, v65
	v_mul_f32_e32 v64, v121, v64
	v_mul_f32_e32 v60, v121, v60
	v_cvt_f32_i32_e32 v61, v61
	v_mul_f32_e32 v64, v72, v64
	v_mul_f32_e32 v60, v68, v60
	v_mul_f32_e32 v64, 0xbfb8aa3b, v64
	v_mul_f32_e32 v60, 0xbfb8aa3b, v60
	v_add_f32_e32 v59, 1.0, v63
	v_add_f32_e32 v63, 1.0, v138
	v_exp_f32_e32 v64, v64
	v_exp_f32_e32 v138, v60
	v_mul_f32_e32 v65, v121, v65
	v_mul_f32_e32 v65, v73, v65
	v_mul_f32_e32 v61, v121, v61
	v_mul_f32_e32 v65, 0xbfb8aa3b, v65
	v_mul_f32_e32 v61, v69, v61
	v_exp_f32_e32 v65, v65
	v_mul_f32_e32 v61, 0xbfb8aa3b, v61
	v_add_f32_e32 v60, 1.0, v64
	v_add_f32_e32 v64, 1.0, v138
	v_exp_f32_e32 v138, v61
	v_add_f32_e32 v61, 1.0, v65
	v_rcp_f32_e32 v58, v58
	v_rcp_f32_e32 v59, v59
	v_rcp_f32_e32 v60, v60
	v_rcp_f32_e32 v61, v61
	v_add_f32_e32 v65, 1.0, v138
	v_rcp_f32_e32 v62, v62
	v_rcp_f32_e32 v63, v63
	v_rcp_f32_e32 v64, v64
	v_rcp_f32_e32 v65, v65
	v_add_u32_e32 v106, 0xb0, v186
	v_ashrrev_i32_e32 v107, 31, v106
	v_lshlrev_b64 v[128:129], 11, v[106:107]
	s_waitcnt vmcnt(5)
	v_cvt_f32_f16_e32 v138, v130
	v_cvt_f32_f16_sdwa v139, v130 dst_sel:DWORD dst_unused:UNUSED_PAD src0_sel:WORD_1
	v_cvt_f32_f16_e32 v130, v131
	v_cvt_f32_f16_sdwa v131, v131 dst_sel:DWORD dst_unused:UNUSED_PAD src0_sel:WORD_1
	s_waitcnt vmcnt(4)
	v_lshlrev_b32_e32 v140, 16, v134
	v_and_b32_e32 v141, 0xffff0000, v134
	v_lshlrev_b32_e32 v134, 16, v135
	v_and_b32_e32 v135, 0xffff0000, v135
	v_pk_fma_f32 v[134:135], v[60:61], v[134:135], v[130:131]
	v_pk_fma_f32 v[138:139], v[58:59], v[140:141], v[138:139]
	v_cvt_f32_f16_e32 v58, v132
	v_cvt_f32_f16_sdwa v59, v132 dst_sel:DWORD dst_unused:UNUSED_PAD src0_sel:WORD_1
	v_cvt_f32_f16_e32 v60, v133
	v_cvt_f32_f16_sdwa v61, v133 dst_sel:DWORD dst_unused:UNUSED_PAD src0_sel:WORD_1
	v_lshlrev_b32_e32 v130, 16, v136
	v_and_b32_e32 v131, 0xffff0000, v136
	v_lshlrev_b32_e32 v132, 16, v137
	v_and_b32_e32 v133, 0xffff0000, v137
	v_pk_fma_f32 v[64:65], v[64:65], v[132:133], v[60:61]
	v_pk_fma_f32 v[132:133], v[62:63], v[130:131], v[58:59]
	v_lshlrev_b64 v[62:63], 12, v[112:113]
	v_lshl_add_u64 v[82:83], v[128:129], 0, v[182:183]
	v_lshl_add_u64 v[62:63], s[16:17], 0, v[62:63]
	v_lshlrev_b64 v[82:83], 1, v[82:83]
	v_cvt_pk_f16_f32 v58, v138, v139
	v_lshl_add_u64 v[130:131], v[62:63], 0, v[184:185]
	v_mov_b32_e32 v62, 0
	v_lshl_add_u64 v[84:85], s[14:15], 0, v[82:83]
	v_lshl_add_u64 v[82:83], s[10:11], 0, v[82:83]
	v_cvt_pk_f16_f32 v59, v134, v135
	v_cvt_pk_f16_f32 v60, v132, v133
	v_cvt_pk_f16_f32 v61, v64, v65
	v_dot2c_f32_f16_e32 v62, v58, v58
	v_mul_f32_e32 v114, 0x41cb3333, v86
	global_load_dwordx4 v[86:89], v[84:85], off
	v_dot2c_f32_f16_e32 v62, v59, v59
	global_load_dwordx4 v[82:85], v[248:249], off offset:2048
	v_pk_fma_f32 v[134:135], v[120:121], v[134:135], s[42:43] op_sel_hi:[0,1,0]
	global_store_dwordx4 v[130:131], v[58:61], off
	v_cvt_f32_i32_e32 v54, v54
	v_cvt_f32_i32_e32 v50, v50
	v_pk_fma_f32 v[58:59], v[120:121], v[138:139], s[42:43] op_sel_hi:[0,1,0]
	v_med3_f32 v58, v58, s93, v221
	v_med3_f32 v59, v59, s93, v221
	v_med3_f32 v63, v134, s93, v221
	v_med3_f32 v134, v135, s93, v221
	v_perm_b32 v63, v134, v63, s1
	v_perm_b32 v58, v59, v58, s1
	v_pk_fma_f32 v[132:133], v[120:121], v[132:133], s[42:43] op_sel_hi:[0,1,0]
	v_pk_fma_f32 v[64:65], v[120:121], v[64:65], s[42:43] op_sel_hi:[0,1,0]
	v_perm_b32 v58, v63, v58, s51
	v_med3_f32 v59, v132, s93, v221
	v_med3_f32 v63, v133, s93, v221
	v_med3_f32 v64, v64, s93, v221
	v_med3_f32 v65, v65, s93, v221
	v_perm_b32 v64, v65, v64, s1
	v_perm_b32 v59, v63, v59, s1
	v_mul_f32_e32 v54, v119, v54
	v_mul_f32_e32 v50, v119, v50
	v_cvt_f32_i32_e32 v55, v55
	v_cvt_f32_i32_e32 v51, v51
	v_perm_b32 v59, v64, v59, s51
	v_lshl_add_u64 v[64:65], s[20:21], 0, v[122:123]
	v_mul_f32_e32 v54, v70, v54
	v_mul_f32_e32 v50, v66, v50
	v_lshl_add_u64 v[132:133], v[64:65], 0, v[182:183]
	v_mul_f32_e32 v54, 0xbfb8aa3b, v54
	v_mul_f32_e32 v50, 0xbfb8aa3b, v50
	global_store_dwordx2 v[132:133], v[58:59], off
	v_exp_f32_e32 v54, v54
	v_exp_f32_e32 v58, v50
	v_mul_f32_e32 v55, v119, v55
	v_mul_f32_e32 v51, v119, v51
	v_cvt_f32_i32_e32 v56, v56
	v_cvt_f32_i32_e32 v52, v52
	v_mul_f32_e32 v55, v71, v55
	v_mul_f32_e32 v51, v67, v51
	v_mul_f32_e32 v55, 0xbfb8aa3b, v55
	v_mul_f32_e32 v51, 0xbfb8aa3b, v51
	v_add_f32_e32 v50, 1.0, v54
	v_add_f32_e32 v54, 1.0, v58
	v_exp_f32_e32 v55, v55
	v_exp_f32_e32 v58, v51
	v_cvt_f32_i32_e32 v57, v57
	v_mul_f32_e32 v56, v119, v56
	v_mul_f32_e32 v52, v119, v52
	v_cvt_f32_i32_e32 v53, v53
	v_mul_f32_e32 v56, v72, v56
	v_mul_f32_e32 v52, v68, v52
	v_mul_f32_e32 v56, 0xbfb8aa3b, v56
	v_mul_f32_e32 v52, 0xbfb8aa3b, v52
	v_add_f32_e32 v51, 1.0, v55
	v_add_f32_e32 v55, 1.0, v58
	v_exp_f32_e32 v56, v56
	v_exp_f32_e32 v58, v52
	v_mul_f32_e32 v57, v119, v57
	v_mul_f32_e32 v57, v73, v57
	v_mul_f32_e32 v53, v119, v53
	v_mul_f32_e32 v57, 0xbfb8aa3b, v57
	v_mul_f32_e32 v53, v69, v53
	v_exp_f32_e32 v57, v57
	v_mul_f32_e32 v53, 0xbfb8aa3b, v53
	v_add_f32_e32 v52, 1.0, v56
	v_add_f32_e32 v56, 1.0, v58
	v_exp_f32_e32 v58, v53
	v_add_f32_e32 v53, 1.0, v57
	v_rcp_f32_e32 v50, v50
	v_rcp_f32_e32 v51, v51
	v_rcp_f32_e32 v52, v52
	v_rcp_f32_e32 v53, v53
	v_add_f32_e32 v57, 1.0, v58
	s_waitcnt vmcnt(7)
	v_cvt_f32_f16_e32 v58, v102
	v_cvt_f32_f16_sdwa v59, v102 dst_sel:DWORD dst_unused:UNUSED_PAD src0_sel:WORD_1
	v_cvt_f32_f16_e32 v64, v103
	v_cvt_f32_f16_sdwa v65, v103 dst_sel:DWORD dst_unused:UNUSED_PAD src0_sel:WORD_1
	s_waitcnt vmcnt(6)
	v_lshlrev_b32_e32 v102, 16, v98
	v_and_b32_e32 v103, 0xffff0000, v98
	v_lshlrev_b32_e32 v98, 16, v99
	v_and_b32_e32 v99, 0xffff0000, v99
	v_rcp_f32_e32 v54, v54
	v_rcp_f32_e32 v55, v55
	v_rcp_f32_e32 v56, v56
	v_rcp_f32_e32 v57, v57
	v_pk_fma_f32 v[64:65], v[52:53], v[98:99], v[64:65]
	v_pk_fma_f32 v[58:59], v[50:51], v[102:103], v[58:59]
	v_cvt_f32_f16_e32 v50, v104
	v_cvt_f32_f16_sdwa v51, v104 dst_sel:DWORD dst_unused:UNUSED_PAD src0_sel:WORD_1
	v_cvt_f32_f16_e32 v52, v105
	v_cvt_f32_f16_sdwa v53, v105 dst_sel:DWORD dst_unused:UNUSED_PAD src0_sel:WORD_1
	v_cvt_f32_i32_e32 v46, v46
	v_cvt_f32_i32_e32 v42, v42
	v_lshlrev_b32_e32 v98, 16, v100
	v_and_b32_e32 v99, 0xffff0000, v100
	v_lshlrev_b32_e32 v100, 16, v101
	v_and_b32_e32 v101, 0xffff0000, v101
	v_pk_fma_f32 v[56:57], v[56:57], v[100:101], v[52:53]
	v_pk_fma_f32 v[54:55], v[54:55], v[98:99], v[50:51]
	v_cvt_pk_f16_f32 v53, v56, v57
	v_cvt_pk_f16_f32 v52, v54, v55
	v_pk_fma_f32 v[54:55], v[118:119], v[54:55], s[42:43] op_sel_hi:[0,1,0]
	v_pk_fma_f32 v[56:57], v[118:119], v[56:57], s[42:43] op_sel_hi:[0,1,0]
	v_cvt_pk_f16_f32 v50, v58, v59
	v_pk_fma_f32 v[58:59], v[118:119], v[58:59], s[42:43] op_sel_hi:[0,1,0]
	v_med3_f32 v54, v54, s93, v221
	v_med3_f32 v55, v55, s93, v221
	v_med3_f32 v56, v56, s93, v221
	v_med3_f32 v57, v57, s93, v221
	v_mul_f32_e32 v46, v117, v46
	v_mul_f32_e32 v42, v117, v42
	v_cvt_f32_i32_e32 v47, v47
	v_cvt_f32_i32_e32 v43, v43
	v_med3_f32 v58, v58, s93, v221
	v_med3_f32 v59, v59, s93, v221
	v_perm_b32 v56, v57, v56, s1
	v_perm_b32 v54, v55, v54, s1
	v_mul_f32_e32 v46, v70, v46
	v_mul_f32_e32 v42, v66, v42
	v_perm_b32 v58, v59, v58, s1
	v_perm_b32 v59, v56, v54, s51
	v_lshl_add_u64 v[54:55], s[20:21], 0, v[124:125]
	v_mul_f32_e32 v46, 0xbfb8aa3b, v46
	v_mul_f32_e32 v42, 0xbfb8aa3b, v42
	v_lshl_add_u64 v[100:101], v[54:55], 0, v[182:183]
	v_exp_f32_e32 v46, v46
	v_exp_f32_e32 v54, v42
	v_mul_f32_e32 v47, v117, v47
	v_mul_f32_e32 v43, v117, v43
	v_cvt_f32_i32_e32 v48, v48
	v_cvt_f32_i32_e32 v44, v44
	v_mul_f32_e32 v47, v71, v47
	v_mul_f32_e32 v43, v67, v43
	v_mul_f32_e32 v47, 0xbfb8aa3b, v47
	v_mul_f32_e32 v43, 0xbfb8aa3b, v43
	v_add_f32_e32 v42, 1.0, v46
	v_add_f32_e32 v46, 1.0, v54
	v_exp_f32_e32 v47, v47
	v_exp_f32_e32 v54, v43
	v_cvt_f32_i32_e32 v49, v49
	v_mul_f32_e32 v48, v117, v48
	v_mul_f32_e32 v44, v117, v44
	v_cvt_f32_i32_e32 v45, v45
	v_mul_f32_e32 v48, v72, v48
	v_mul_f32_e32 v44, v68, v44
	v_mul_f32_e32 v48, 0xbfb8aa3b, v48
	v_mul_f32_e32 v44, 0xbfb8aa3b, v44
	v_add_f32_e32 v43, 1.0, v47
	v_add_f32_e32 v47, 1.0, v54
	v_exp_f32_e32 v48, v48
	v_exp_f32_e32 v54, v44
	v_mul_f32_e32 v49, v117, v49
	v_mul_f32_e32 v49, v73, v49
	v_mul_f32_e32 v45, v117, v45
	v_mul_f32_e32 v49, 0xbfb8aa3b, v49
	v_mul_f32_e32 v45, v69, v45
	v_exp_f32_e32 v49, v49
	v_mul_f32_e32 v45, 0xbfb8aa3b, v45
	v_add_f32_e32 v44, 1.0, v48
	v_add_f32_e32 v48, 1.0, v54
	v_exp_f32_e32 v54, v45
	v_cvt_pk_f16_f32 v51, v64, v65
	v_pk_fma_f32 v[64:65], v[118:119], v[64:65], s[42:43] op_sel_hi:[0,1,0]
	v_add_f32_e32 v45, 1.0, v49
	v_lshlrev_b64 v[98:99], 12, v[110:111]
	v_med3_f32 v63, v64, s93, v221
	v_med3_f32 v64, v65, s93, v221
	v_rcp_f32_e32 v42, v42
	v_rcp_f32_e32 v43, v43
	v_rcp_f32_e32 v44, v44
	v_rcp_f32_e32 v45, v45
	v_add_f32_e32 v49, 1.0, v54
	s_waitcnt vmcnt(5)
	v_cvt_f32_f16_e32 v54, v94
	v_cvt_f32_f16_sdwa v55, v94 dst_sel:DWORD dst_unused:UNUSED_PAD src0_sel:WORD_1
	v_cvt_f32_f16_e32 v56, v95
	v_cvt_f32_f16_sdwa v57, v95 dst_sel:DWORD dst_unused:UNUSED_PAD src0_sel:WORD_1
	v_lshl_add_u64 v[98:99], s[16:17], 0, v[98:99]
	v_perm_b32 v63, v64, v63, s1
	v_lshl_add_u64 v[98:99], v[98:99], 0, v[184:185]
	v_perm_b32 v58, v63, v58, s51
	global_store_dwordx4 v[98:99], v[50:53], off
	global_store_dwordx2 v[100:101], v[58:59], off
	s_waitcnt vmcnt(6)
	v_lshlrev_b32_e32 v58, 16, v90
	v_and_b32_e32 v59, 0xffff0000, v90
	v_lshlrev_b32_e32 v64, 16, v91
	v_and_b32_e32 v65, 0xffff0000, v91
	v_rcp_f32_e32 v46, v46
	v_rcp_f32_e32 v47, v47
	v_rcp_f32_e32 v48, v48
	v_rcp_f32_e32 v49, v49
	v_pk_fma_f32 v[56:57], v[44:45], v[64:65], v[56:57]
	v_pk_fma_f32 v[54:55], v[42:43], v[58:59], v[54:55]
	v_cvt_f32_f16_e32 v42, v96
	v_cvt_f32_f16_sdwa v43, v96 dst_sel:DWORD dst_unused:UNUSED_PAD src0_sel:WORD_1
	v_cvt_f32_f16_e32 v44, v97
	v_cvt_f32_f16_sdwa v45, v97 dst_sel:DWORD dst_unused:UNUSED_PAD src0_sel:WORD_1
	v_cvt_f32_i32_e32 v38, v38
	v_cvt_f32_i32_e32 v34, v34
	v_lshlrev_b32_e32 v58, 16, v92
	v_and_b32_e32 v59, 0xffff0000, v92
	v_lshlrev_b32_e32 v64, 16, v93
	v_and_b32_e32 v65, 0xffff0000, v93
	v_pk_fma_f32 v[48:49], v[48:49], v[64:65], v[44:45]
	v_pk_fma_f32 v[46:47], v[46:47], v[58:59], v[42:43]
	v_cvt_pk_f16_f32 v45, v48, v49
	v_cvt_pk_f16_f32 v44, v46, v47
	v_pk_fma_f32 v[46:47], v[116:117], v[46:47], s[42:43] op_sel_hi:[0,1,0]
	v_pk_fma_f32 v[48:49], v[116:117], v[48:49], s[42:43] op_sel_hi:[0,1,0]
	v_cvt_pk_f16_f32 v42, v54, v55
	v_pk_fma_f32 v[54:55], v[116:117], v[54:55], s[42:43] op_sel_hi:[0,1,0]
	v_med3_f32 v46, v46, s93, v221
	v_med3_f32 v47, v47, s93, v221
	v_med3_f32 v48, v48, s93, v221
	v_med3_f32 v49, v49, s93, v221
	v_mul_f32_e32 v38, v115, v38
	v_mul_f32_e32 v34, v115, v34
	v_cvt_f32_i32_e32 v39, v39
	v_cvt_f32_i32_e32 v35, v35
	v_med3_f32 v54, v54, s93, v221
	v_med3_f32 v55, v55, s93, v221
	v_perm_b32 v48, v49, v48, s1
	v_perm_b32 v46, v47, v46, s1
	v_mul_f32_e32 v38, v70, v38
	v_mul_f32_e32 v34, v66, v34
	v_perm_b32 v54, v55, v54, s1
	v_perm_b32 v55, v48, v46, s51
	v_lshl_add_u64 v[46:47], s[20:21], 0, v[126:127]
	v_mul_f32_e32 v38, 0xbfb8aa3b, v38
	v_mul_f32_e32 v34, 0xbfb8aa3b, v34
	v_lshl_add_u64 v[92:93], v[46:47], 0, v[182:183]
	v_exp_f32_e32 v38, v38
	v_exp_f32_e32 v46, v34
	v_mul_f32_e32 v39, v115, v39
	v_mul_f32_e32 v35, v115, v35
	v_cvt_f32_i32_e32 v40, v40
	v_cvt_f32_i32_e32 v36, v36
	v_mul_f32_e32 v39, v71, v39
	v_mul_f32_e32 v35, v67, v35
	v_mul_f32_e32 v39, 0xbfb8aa3b, v39
	v_mul_f32_e32 v35, 0xbfb8aa3b, v35
	v_add_f32_e32 v34, 1.0, v38
	v_add_f32_e32 v38, 1.0, v46
	v_exp_f32_e32 v39, v39
	v_exp_f32_e32 v46, v35
	v_cvt_f32_i32_e32 v41, v41
	v_mul_f32_e32 v40, v115, v40
	v_mul_f32_e32 v36, v115, v36
	v_cvt_f32_i32_e32 v37, v37
	v_mul_f32_e32 v40, v72, v40
	v_mul_f32_e32 v36, v68, v36
	v_mul_f32_e32 v40, 0xbfb8aa3b, v40
	v_mul_f32_e32 v36, 0xbfb8aa3b, v36
	v_add_f32_e32 v35, 1.0, v39
	v_add_f32_e32 v39, 1.0, v46
	v_exp_f32_e32 v40, v40
	v_exp_f32_e32 v46, v36
	v_mul_f32_e32 v41, v115, v41
	v_mul_f32_e32 v41, v73, v41
	v_mul_f32_e32 v37, v115, v37
	v_mul_f32_e32 v41, 0xbfb8aa3b, v41
	v_mul_f32_e32 v37, v69, v37
	v_exp_f32_e32 v41, v41
	v_mul_f32_e32 v37, 0xbfb8aa3b, v37
	v_add_f32_e32 v36, 1.0, v40
	v_add_f32_e32 v40, 1.0, v46
	v_exp_f32_e32 v46, v37
	v_cvt_pk_f16_f32 v43, v56, v57
	v_pk_fma_f32 v[56:57], v[116:117], v[56:57], s[42:43] op_sel_hi:[0,1,0]
	v_add_f32_e32 v37, 1.0, v41
	v_lshlrev_b64 v[58:59], 12, v[108:109]
	v_med3_f32 v56, v56, s93, v221
	v_med3_f32 v57, v57, s93, v221
	v_rcp_f32_e32 v34, v34
	v_rcp_f32_e32 v35, v35
	v_rcp_f32_e32 v36, v36
	v_rcp_f32_e32 v37, v37
	v_add_f32_e32 v41, 1.0, v46
	s_waitcnt vmcnt(5)
	v_cvt_f32_f16_e32 v46, v86
	v_cvt_f32_f16_sdwa v47, v86 dst_sel:DWORD dst_unused:UNUSED_PAD src0_sel:WORD_1
	v_cvt_f32_f16_e32 v48, v87
	v_cvt_f32_f16_sdwa v49, v87 dst_sel:DWORD dst_unused:UNUSED_PAD src0_sel:WORD_1
	v_lshl_add_u64 v[58:59], s[16:17], 0, v[58:59]
	v_perm_b32 v56, v57, v56, s1
	v_lshl_add_u64 v[90:91], v[58:59], 0, v[184:185]
	v_perm_b32 v54, v56, v54, s51
	global_store_dwordx4 v[90:91], v[42:45], off
	global_store_dwordx2 v[92:93], v[54:55], off
	s_waitcnt vmcnt(6)
	v_lshlrev_b32_e32 v54, 16, v82
	v_and_b32_e32 v55, 0xffff0000, v82
	v_lshlrev_b32_e32 v56, 16, v83
	v_and_b32_e32 v57, 0xffff0000, v83
	v_rcp_f32_e32 v38, v38
	v_rcp_f32_e32 v39, v39
	v_rcp_f32_e32 v40, v40
	v_rcp_f32_e32 v41, v41
	v_pk_fma_f32 v[48:49], v[36:37], v[56:57], v[48:49]
	v_pk_fma_f32 v[46:47], v[34:35], v[54:55], v[46:47]
	v_cvt_f32_f16_e32 v34, v88
	v_cvt_f32_f16_sdwa v35, v88 dst_sel:DWORD dst_unused:UNUSED_PAD src0_sel:WORD_1
	v_cvt_f32_f16_e32 v36, v89
	v_cvt_f32_f16_sdwa v37, v89 dst_sel:DWORD dst_unused:UNUSED_PAD src0_sel:WORD_1
	v_lshlrev_b32_e32 v54, 16, v84
	v_and_b32_e32 v55, 0xffff0000, v84
	v_lshlrev_b32_e32 v56, 16, v85
	v_and_b32_e32 v57, 0xffff0000, v85
	v_pk_fma_f32 v[40:41], v[40:41], v[56:57], v[36:37]
	v_pk_fma_f32 v[38:39], v[38:39], v[54:55], v[34:35]
	v_cvt_pk_f16_f32 v37, v40, v41
	v_cvt_pk_f16_f32 v36, v38, v39
	v_pk_fma_f32 v[38:39], v[114:115], v[38:39], s[42:43] op_sel_hi:[0,1,0]
	v_pk_fma_f32 v[40:41], v[114:115], v[40:41], s[42:43] op_sel_hi:[0,1,0]
	v_cvt_pk_f16_f32 v34, v46, v47
	v_pk_fma_f32 v[46:47], v[114:115], v[46:47], s[42:43] op_sel_hi:[0,1,0]
	v_med3_f32 v38, v38, s93, v221
	v_med3_f32 v39, v39, s93, v221
	v_med3_f32 v40, v40, s93, v221
	v_med3_f32 v41, v41, s93, v221
	v_cvt_pk_f16_f32 v35, v48, v49
	v_pk_fma_f32 v[48:49], v[114:115], v[48:49], s[42:43] op_sel_hi:[0,1,0]
	v_med3_f32 v46, v46, s93, v221
	v_med3_f32 v47, v47, s93, v221
	v_perm_b32 v40, v41, v40, s1
	v_perm_b32 v38, v39, v38, s1
	v_lshlrev_b64 v[54:55], 12, v[106:107]
	v_med3_f32 v48, v48, s93, v221
	v_med3_f32 v49, v49, s93, v221
	v_perm_b32 v46, v47, v46, s1
	v_perm_b32 v47, v40, v38, s51
	v_lshl_add_u64 v[38:39], s[20:21], 0, v[128:129]
	v_lshl_add_u64 v[54:55], s[16:17], 0, v[54:55]
	v_perm_b32 v48, v49, v48, s1
	v_lshl_add_u64 v[70:71], v[38:39], 0, v[182:183]
	v_lshl_add_u64 v[38:39], v[122:123], 0, v[150:151]
	v_lshl_add_u64 v[72:73], v[54:55], 0, v[184:185]
	v_perm_b32 v46, v48, v46, s51
	v_lshlrev_b64 v[38:39], 1, v[38:39]
	global_store_dwordx4 v[72:73], v[34:37], off
	global_store_dwordx2 v[70:71], v[46:47], off
	v_lshl_add_u64 v[40:41], s[14:15], 0, v[38:39]
	global_load_dwordx4 v[82:85], v[40:41], off
	v_lshl_add_u64 v[38:39], s[10:11], 0, v[38:39]
	global_load_dwordx4 v[86:89], v[246:247], off offset:1024
	v_lshl_add_u64 v[38:39], v[124:125], 0, v[150:151]
	v_lshlrev_b64 v[38:39], 1, v[38:39]
	v_lshl_add_u64 v[40:41], s[14:15], 0, v[38:39]
	global_load_dwordx4 v[66:69], v[40:41], off
	v_dot2c_f32_f16_e32 v62, v60, v60
	v_dot2c_f32_f16_e32 v62, v61, v61
	v_lshl_add_u64 v[38:39], s[10:11], 0, v[38:39]
	v_cvt_f32_i32_e32 v30, v30
	v_cvt_f32_i32_e32 v26, v26
	v_add_f32_e32 v102, 0, v62
	global_load_dwordx4 v[62:65], v[246:247], off offset:3072
	v_lshl_add_u64 v[38:39], v[126:127], 0, v[150:151]
	v_lshlrev_b64 v[38:39], 1, v[38:39]
	v_mul_f32_e32 v30, v121, v30
	v_mul_f32_e32 v26, v121, v26
	v_cvt_f32_i32_e32 v31, v31
	v_cvt_f32_i32_e32 v27, v27
	v_lshl_add_u64 v[40:41], s[14:15], 0, v[38:39]
	v_mul_f32_e32 v30, v78, v30
	v_mul_f32_e32 v26, v74, v26
	global_load_dwordx4 v[58:61], v[40:41], off
	v_mul_f32_e32 v30, 0xbfb8aa3b, v30
	v_mul_f32_e32 v26, 0xbfb8aa3b, v26
	v_exp_f32_e32 v30, v30
	v_exp_f32_e32 v94, v26
	v_lshl_add_u64 v[38:39], s[10:11], 0, v[38:39]
	v_mul_f32_e32 v31, v121, v31
	v_mul_f32_e32 v27, v121, v27
	v_cvt_f32_i32_e32 v32, v32
	v_cvt_f32_i32_e32 v28, v28
	global_load_dwordx4 v[54:57], v[248:249], off offset:1024
	v_mul_f32_e32 v31, v79, v31
	v_mul_f32_e32 v27, v75, v27
	v_mul_f32_e32 v31, 0xbfb8aa3b, v31
	v_mul_f32_e32 v27, 0xbfb8aa3b, v27
	v_add_f32_e32 v26, 1.0, v30
	v_add_f32_e32 v30, 1.0, v94
	v_exp_f32_e32 v31, v31
	v_exp_f32_e32 v94, v27
	v_cvt_f32_i32_e32 v33, v33
	v_mul_f32_e32 v32, v121, v32
	v_mul_f32_e32 v28, v121, v28
	v_cvt_f32_i32_e32 v29, v29
	v_mul_f32_e32 v32, v80, v32
	v_mul_f32_e32 v28, v76, v28
	v_mul_f32_e32 v32, 0xbfb8aa3b, v32
	v_mul_f32_e32 v28, 0xbfb8aa3b, v28
	v_add_f32_e32 v27, 1.0, v31
	v_add_f32_e32 v31, 1.0, v94
	v_exp_f32_e32 v32, v32
	v_exp_f32_e32 v94, v28
	v_mul_f32_e32 v33, v121, v33
	v_mul_f32_e32 v33, v81, v33
	v_mul_f32_e32 v29, v121, v29
	v_mul_f32_e32 v33, 0xbfb8aa3b, v33
	v_mul_f32_e32 v29, v77, v29
	v_exp_f32_e32 v33, v33
	v_mul_f32_e32 v29, 0xbfb8aa3b, v29
	v_add_f32_e32 v28, 1.0, v32
	v_add_f32_e32 v32, 1.0, v94
	v_exp_f32_e32 v94, v29
	v_add_f32_e32 v29, 1.0, v33
	v_rcp_f32_e32 v26, v26
	v_rcp_f32_e32 v27, v27
	v_rcp_f32_e32 v28, v28
	v_rcp_f32_e32 v29, v29
	v_add_f32_e32 v33, 1.0, v94
	v_rcp_f32_e32 v30, v30
	v_rcp_f32_e32 v31, v31
	v_rcp_f32_e32 v32, v32
	v_rcp_f32_e32 v33, v33
	v_lshl_add_u64 v[38:39], v[128:129], 0, v[150:151]
	v_lshlrev_b64 v[38:39], 1, v[38:39]
	v_lshl_add_u64 v[40:41], s[14:15], 0, v[38:39]
	global_load_dwordx4 v[46:49], v[40:41], off
	v_lshl_add_u64 v[38:39], s[10:11], 0, v[38:39]
	global_load_dwordx4 v[38:41], v[248:249], off offset:3072
	s_waitcnt vmcnt(7)
	v_cvt_f32_f16_e32 v94, v82
	v_cvt_f32_f16_sdwa v95, v82 dst_sel:DWORD dst_unused:UNUSED_PAD src0_sel:WORD_1
	v_cvt_f32_f16_e32 v82, v83
	v_cvt_f32_f16_sdwa v83, v83 dst_sel:DWORD dst_unused:UNUSED_PAD src0_sel:WORD_1
	s_waitcnt vmcnt(6)
	v_lshlrev_b32_e32 v96, 16, v86
	v_and_b32_e32 v97, 0xffff0000, v86
	v_lshlrev_b32_e32 v86, 16, v87
	v_and_b32_e32 v87, 0xffff0000, v87
	v_pk_fma_f32 v[82:83], v[28:29], v[86:87], v[82:83]
	v_pk_fma_f32 v[86:87], v[26:27], v[96:97], v[94:95]
	v_cvt_f32_f16_e32 v26, v84
	v_cvt_f32_f16_sdwa v27, v84 dst_sel:DWORD dst_unused:UNUSED_PAD src0_sel:WORD_1
	v_cvt_f32_f16_e32 v28, v85
	v_cvt_f32_f16_sdwa v29, v85 dst_sel:DWORD dst_unused:UNUSED_PAD src0_sel:WORD_1
	v_lshlrev_b32_e32 v84, 16, v88
	v_and_b32_e32 v85, 0xffff0000, v88
	v_pk_fma_f32 v[30:31], v[30:31], v[84:85], v[26:27]
	v_cvt_pk_f16_f32 v26, v86, v87
	v_mov_b32_e32 v84, 0
	v_lshlrev_b32_e32 v88, 16, v89
	v_and_b32_e32 v89, 0xffff0000, v89
	v_cvt_pk_f16_f32 v27, v82, v83
	v_dot2c_f32_f16_e32 v84, v26, v26
	v_pk_fma_f32 v[32:33], v[32:33], v[88:89], v[28:29]
	v_cvt_pk_f16_f32 v28, v30, v31
	v_dot2c_f32_f16_e32 v84, v27, v27
	v_cvt_pk_f16_f32 v29, v32, v33
	v_dot2c_f32_f16_e32 v84, v28, v28
	global_store_dwordx4 v[130:131], v[26:29], off offset:256
	v_dot2c_f32_f16_e32 v84, v29, v29
	v_cvt_f32_i32_e32 v22, v22
	v_pk_fma_f32 v[26:27], v[120:121], v[86:87], s[42:43] op_sel_hi:[0,1,0]
	v_pk_fma_f32 v[28:29], v[120:121], v[82:83], s[42:43] op_sel_hi:[0,1,0]
	v_cvt_f32_i32_e32 v18, v18
	v_med3_f32 v26, v26, s93, v221
	v_med3_f32 v27, v27, s93, v221
	v_med3_f32 v28, v28, s93, v221
	v_med3_f32 v29, v29, s93, v221
	v_perm_b32 v28, v29, v28, s1
	v_perm_b32 v26, v27, v26, s1
	v_perm_b32 v26, v28, v26, s51
	v_pk_fma_f32 v[28:29], v[120:121], v[30:31], s[42:43] op_sel_hi:[0,1,0]
	v_pk_fma_f32 v[30:31], v[120:121], v[32:33], s[42:43] op_sel_hi:[0,1,0]
	v_med3_f32 v27, v28, s93, v221
	v_med3_f32 v28, v29, s93, v221
	v_med3_f32 v29, v30, s93, v221
	v_med3_f32 v30, v31, s93, v221
	v_mul_f32_e32 v22, v119, v22
	v_mul_f32_e32 v18, v119, v18
	v_cvt_f32_i32_e32 v23, v23
	v_cvt_f32_i32_e32 v19, v19
	v_perm_b32 v29, v30, v29, s1
	v_perm_b32 v27, v28, v27, s1
	v_mul_f32_e32 v22, v78, v22
	v_mul_f32_e32 v18, v74, v18
	v_perm_b32 v27, v29, v27, s51
	v_mul_f32_e32 v22, 0xbfb8aa3b, v22
	v_mul_f32_e32 v18, 0xbfb8aa3b, v18
	global_store_dwordx2 v[132:133], v[26:27], off offset:128
	v_exp_f32_e32 v22, v22
	v_exp_f32_e32 v26, v18
	v_mul_f32_e32 v23, v119, v23
	v_mul_f32_e32 v19, v119, v19
	v_cvt_f32_i32_e32 v24, v24
	v_cvt_f32_i32_e32 v20, v20
	v_mul_f32_e32 v23, v79, v23
	v_mul_f32_e32 v19, v75, v19
	v_mul_f32_e32 v23, 0xbfb8aa3b, v23
	v_mul_f32_e32 v19, 0xbfb8aa3b, v19
	v_add_f32_e32 v18, 1.0, v22
	v_add_f32_e32 v22, 1.0, v26
	v_exp_f32_e32 v23, v23
	v_exp_f32_e32 v26, v19
	v_cvt_f32_i32_e32 v25, v25
	v_mul_f32_e32 v24, v119, v24
	v_mul_f32_e32 v20, v119, v20
	v_cvt_f32_i32_e32 v21, v21
	v_mul_f32_e32 v24, v80, v24
	v_mul_f32_e32 v20, v76, v20
	v_mul_f32_e32 v24, 0xbfb8aa3b, v24
	v_mul_f32_e32 v20, 0xbfb8aa3b, v20
	v_add_f32_e32 v19, 1.0, v23
	v_add_f32_e32 v23, 1.0, v26
	v_exp_f32_e32 v24, v24
	v_exp_f32_e32 v26, v20
	v_mul_f32_e32 v25, v119, v25
	v_mul_f32_e32 v25, v81, v25
	v_mul_f32_e32 v21, v119, v21
	v_mul_f32_e32 v25, 0xbfb8aa3b, v25
	v_mul_f32_e32 v21, v77, v21
	v_exp_f32_e32 v25, v25
	v_mul_f32_e32 v21, 0xbfb8aa3b, v21
	v_add_f32_e32 v20, 1.0, v24
	v_add_f32_e32 v24, 1.0, v26
	v_exp_f32_e32 v26, v21
	v_add_f32_e32 v21, 1.0, v25
	v_rcp_f32_e32 v18, v18
	v_rcp_f32_e32 v19, v19
	v_rcp_f32_e32 v20, v20
	v_rcp_f32_e32 v21, v21
	v_add_f32_e32 v25, 1.0, v26
	s_waitcnt vmcnt(7)
	v_cvt_f32_f16_e32 v26, v66
	v_cvt_f32_f16_sdwa v27, v66 dst_sel:DWORD dst_unused:UNUSED_PAD src0_sel:WORD_1
	v_cvt_f32_f16_e32 v28, v67
	v_cvt_f32_f16_sdwa v29, v67 dst_sel:DWORD dst_unused:UNUSED_PAD src0_sel:WORD_1
	s_waitcnt vmcnt(6)
	v_lshlrev_b32_e32 v30, 16, v62
	v_and_b32_e32 v31, 0xffff0000, v62
	v_lshlrev_b32_e32 v32, 16, v63
	v_and_b32_e32 v33, 0xffff0000, v63
	v_rcp_f32_e32 v22, v22
	v_rcp_f32_e32 v23, v23
	v_rcp_f32_e32 v24, v24
	v_rcp_f32_e32 v25, v25
	v_pk_fma_f32 v[28:29], v[20:21], v[32:33], v[28:29]
	v_pk_fma_f32 v[26:27], v[18:19], v[30:31], v[26:27]
	v_cvt_f32_f16_e32 v18, v68
	v_cvt_f32_f16_sdwa v19, v68 dst_sel:DWORD dst_unused:UNUSED_PAD src0_sel:WORD_1
	v_cvt_f32_f16_e32 v20, v69
	v_cvt_f32_f16_sdwa v21, v69 dst_sel:DWORD dst_unused:UNUSED_PAD src0_sel:WORD_1
	v_cvt_f32_i32_e32 v14, v14
	v_cvt_f32_i32_e32 v10, v10
	v_lshlrev_b32_e32 v30, 16, v64
	v_and_b32_e32 v31, 0xffff0000, v64
	v_lshlrev_b32_e32 v32, 16, v65
	v_and_b32_e32 v33, 0xffff0000, v65
	v_pk_fma_f32 v[24:25], v[24:25], v[32:33], v[20:21]
	v_pk_fma_f32 v[22:23], v[22:23], v[30:31], v[18:19]
	v_cvt_pk_f16_f32 v21, v24, v25
	v_cvt_pk_f16_f32 v20, v22, v23
	v_pk_fma_f32 v[22:23], v[118:119], v[22:23], s[42:43] op_sel_hi:[0,1,0]
	v_pk_fma_f32 v[24:25], v[118:119], v[24:25], s[42:43] op_sel_hi:[0,1,0]
	v_mul_f32_e32 v14, v117, v14
	v_mul_f32_e32 v10, v117, v10
	v_cvt_f32_i32_e32 v15, v15
	v_cvt_f32_i32_e32 v11, v11
	v_cvt_pk_f16_f32 v18, v26, v27
	v_pk_fma_f32 v[26:27], v[118:119], v[26:27], s[42:43] op_sel_hi:[0,1,0]
	v_med3_f32 v22, v22, s93, v221
	v_med3_f32 v23, v23, s93, v221
	v_med3_f32 v24, v24, s93, v221
	v_med3_f32 v25, v25, s93, v221
	v_mul_f32_e32 v14, v78, v14
	v_mul_f32_e32 v10, v74, v10
	v_med3_f32 v26, v26, s93, v221
	v_med3_f32 v27, v27, s93, v221
	v_perm_b32 v24, v25, v24, s1
	v_perm_b32 v22, v23, v22, s1
	v_mul_f32_e32 v14, 0xbfb8aa3b, v14
	v_mul_f32_e32 v10, 0xbfb8aa3b, v10
	v_perm_b32 v26, v27, v26, s1
	v_perm_b32 v27, v24, v22, s51
	v_exp_f32_e32 v14, v14
	v_exp_f32_e32 v22, v10
	v_mul_f32_e32 v15, v117, v15
	v_mul_f32_e32 v11, v117, v11
	v_cvt_f32_i32_e32 v16, v16
	v_cvt_f32_i32_e32 v12, v12
	v_mul_f32_e32 v15, v79, v15
	v_mul_f32_e32 v11, v75, v11
	v_mul_f32_e32 v15, 0xbfb8aa3b, v15
	v_mul_f32_e32 v11, 0xbfb8aa3b, v11
	v_add_f32_e32 v10, 1.0, v14
	v_add_f32_e32 v14, 1.0, v22
	v_exp_f32_e32 v15, v15
	v_exp_f32_e32 v22, v11
	v_cvt_f32_i32_e32 v17, v17
	v_mul_f32_e32 v16, v117, v16
	v_mul_f32_e32 v12, v117, v12
	v_cvt_f32_i32_e32 v13, v13
	v_mul_f32_e32 v16, v80, v16
	v_mul_f32_e32 v12, v76, v12
	v_mul_f32_e32 v16, 0xbfb8aa3b, v16
	v_mul_f32_e32 v12, 0xbfb8aa3b, v12
	v_add_f32_e32 v11, 1.0, v15
	v_add_f32_e32 v15, 1.0, v22
	v_exp_f32_e32 v16, v16
	v_exp_f32_e32 v22, v12
	v_mul_f32_e32 v17, v117, v17
	v_mul_f32_e32 v17, v81, v17
	v_mul_f32_e32 v13, v117, v13
	v_mul_f32_e32 v17, 0xbfb8aa3b, v17
	v_mul_f32_e32 v13, v77, v13
	v_exp_f32_e32 v17, v17
	v_mul_f32_e32 v13, 0xbfb8aa3b, v13
	v_add_f32_e32 v12, 1.0, v16
	v_add_f32_e32 v16, 1.0, v22
	v_exp_f32_e32 v22, v13
	v_cvt_pk_f16_f32 v19, v28, v29
	v_pk_fma_f32 v[28:29], v[118:119], v[28:29], s[42:43] op_sel_hi:[0,1,0]
	v_add_f32_e32 v13, 1.0, v17
	v_med3_f32 v28, v28, s93, v221
	v_med3_f32 v29, v29, s93, v221
	v_rcp_f32_e32 v10, v10
	v_rcp_f32_e32 v11, v11
	v_rcp_f32_e32 v12, v12
	v_rcp_f32_e32 v13, v13
	v_add_f32_e32 v17, 1.0, v22
	s_waitcnt vmcnt(5)
	v_cvt_f32_f16_e32 v22, v58
	v_cvt_f32_f16_sdwa v23, v58 dst_sel:DWORD dst_unused:UNUSED_PAD src0_sel:WORD_1
	v_cvt_f32_f16_e32 v24, v59
	v_cvt_f32_f16_sdwa v25, v59 dst_sel:DWORD dst_unused:UNUSED_PAD src0_sel:WORD_1
	v_perm_b32 v28, v29, v28, s1
	v_perm_b32 v26, v28, v26, s51
	global_store_dwordx4 v[98:99], v[18:21], off offset:256
	global_store_dwordx2 v[100:101], v[26:27], off offset:128
	s_waitcnt vmcnt(6)
	v_lshlrev_b32_e32 v26, 16, v54
	v_and_b32_e32 v27, 0xffff0000, v54
	v_lshlrev_b32_e32 v28, 16, v55
	v_and_b32_e32 v29, 0xffff0000, v55
	v_rcp_f32_e32 v14, v14
	v_rcp_f32_e32 v15, v15
	v_rcp_f32_e32 v16, v16
	v_rcp_f32_e32 v17, v17
	v_pk_fma_f32 v[24:25], v[12:13], v[28:29], v[24:25]
	v_pk_fma_f32 v[22:23], v[10:11], v[26:27], v[22:23]
	v_cvt_f32_f16_e32 v10, v60
	v_cvt_f32_f16_sdwa v11, v60 dst_sel:DWORD dst_unused:UNUSED_PAD src0_sel:WORD_1
	v_cvt_f32_f16_e32 v12, v61
	v_cvt_f32_f16_sdwa v13, v61 dst_sel:DWORD dst_unused:UNUSED_PAD src0_sel:WORD_1
	v_cvt_f32_i32_e32 v6, v6
	v_cvt_f32_i32_e32 v2, v2
	v_lshlrev_b32_e32 v26, 16, v56
	v_and_b32_e32 v27, 0xffff0000, v56
	v_lshlrev_b32_e32 v28, 16, v57
	v_and_b32_e32 v29, 0xffff0000, v57
	v_pk_fma_f32 v[16:17], v[16:17], v[28:29], v[12:13]
	v_pk_fma_f32 v[14:15], v[14:15], v[26:27], v[10:11]
	v_cvt_pk_f16_f32 v13, v16, v17
	v_cvt_pk_f16_f32 v12, v14, v15
	v_pk_fma_f32 v[14:15], v[116:117], v[14:15], s[42:43] op_sel_hi:[0,1,0]
	v_pk_fma_f32 v[16:17], v[116:117], v[16:17], s[42:43] op_sel_hi:[0,1,0]
	v_mul_f32_e32 v6, v115, v6
	v_mul_f32_e32 v2, v115, v2
	v_cvt_f32_i32_e32 v7, v7
	v_cvt_f32_i32_e32 v3, v3
	v_cvt_pk_f16_f32 v10, v22, v23
	v_pk_fma_f32 v[22:23], v[116:117], v[22:23], s[42:43] op_sel_hi:[0,1,0]
	v_med3_f32 v14, v14, s93, v221
	v_med3_f32 v15, v15, s93, v221
	v_med3_f32 v16, v16, s93, v221
	v_med3_f32 v17, v17, s93, v221
	v_mul_f32_e32 v6, v78, v6
	v_mul_f32_e32 v2, v74, v2
	v_med3_f32 v22, v22, s93, v221
	v_med3_f32 v23, v23, s93, v221
	v_perm_b32 v16, v17, v16, s1
	v_perm_b32 v14, v15, v14, s1
	v_mul_f32_e32 v6, 0xbfb8aa3b, v6
	v_mul_f32_e32 v2, 0xbfb8aa3b, v2
	v_perm_b32 v22, v23, v22, s1
	v_perm_b32 v23, v16, v14, s51
	v_exp_f32_e32 v6, v6
	v_exp_f32_e32 v14, v2
	v_mul_f32_e32 v7, v115, v7
	v_mul_f32_e32 v3, v115, v3
	v_cvt_f32_i32_e32 v8, v8
	v_cvt_f32_i32_e32 v4, v4
	v_mul_f32_e32 v7, v79, v7
	v_mul_f32_e32 v3, v75, v3
	v_mul_f32_e32 v7, 0xbfb8aa3b, v7
	v_mul_f32_e32 v3, 0xbfb8aa3b, v3
	v_add_f32_e32 v2, 1.0, v6
	v_add_f32_e32 v6, 1.0, v14
	v_exp_f32_e32 v7, v7
	v_exp_f32_e32 v14, v3
	v_mul_f32_e32 v8, v115, v8
	v_mul_f32_e32 v4, v115, v4
	v_cvt_f32_i32_e32 v9, v9
	v_cvt_f32_i32_e32 v5, v5
	v_mul_f32_e32 v8, v80, v8
	v_mul_f32_e32 v4, v76, v4
	v_mul_f32_e32 v8, 0xbfb8aa3b, v8
	v_mul_f32_e32 v4, 0xbfb8aa3b, v4
	v_add_f32_e32 v3, 1.0, v7
	v_add_f32_e32 v7, 1.0, v14
	v_exp_f32_e32 v8, v8
	v_exp_f32_e32 v14, v4
	v_mul_f32_e32 v9, v115, v9
	v_mul_f32_e32 v5, v115, v5
	v_mul_f32_e32 v9, v81, v9
	v_mul_f32_e32 v5, v77, v5
	v_mul_f32_e32 v9, 0xbfb8aa3b, v9
	v_mul_f32_e32 v5, 0xbfb8aa3b, v5
	v_add_f32_e32 v4, 1.0, v8
	v_add_f32_e32 v8, 1.0, v14
	v_exp_f32_e32 v9, v9
	v_exp_f32_e32 v14, v5
	v_cvt_pk_f16_f32 v11, v24, v25
	v_pk_fma_f32 v[24:25], v[116:117], v[24:25], s[42:43] op_sel_hi:[0,1,0]
	v_med3_f32 v24, v24, s93, v221
	v_med3_f32 v25, v25, s93, v221
	v_rcp_f32_e32 v2, v2
	v_rcp_f32_e32 v3, v3
	v_add_f32_e32 v5, 1.0, v9
	v_add_f32_e32 v9, 1.0, v14
	s_waitcnt vmcnt(5)
	v_cvt_f32_f16_e32 v14, v46
	v_cvt_f32_f16_sdwa v15, v46 dst_sel:DWORD dst_unused:UNUSED_PAD src0_sel:WORD_1
	v_perm_b32 v24, v25, v24, s1
	v_perm_b32 v22, v24, v22, s51
	global_store_dwordx4 v[90:91], v[10:13], off offset:256
	global_store_dwordx2 v[92:93], v[22:23], off offset:128
	s_waitcnt vmcnt(6)
	v_lshlrev_b32_e32 v22, 16, v38
	v_and_b32_e32 v23, 0xffff0000, v38
	v_rcp_f32_e32 v6, v6
	v_rcp_f32_e32 v7, v7
	v_pk_fma_f32 v[14:15], v[2:3], v[22:23], v[14:15]
	v_cvt_f32_f16_e32 v2, v48
	v_cvt_f32_f16_sdwa v3, v48 dst_sel:DWORD dst_unused:UNUSED_PAD src0_sel:WORD_1
	v_rcp_f32_e32 v4, v4
	v_rcp_f32_e32 v5, v5
	v_cvt_f32_f16_e32 v16, v47
	v_cvt_f32_f16_sdwa v17, v47 dst_sel:DWORD dst_unused:UNUSED_PAD src0_sel:WORD_1
	v_lshlrev_b32_e32 v22, 16, v40
	v_and_b32_e32 v23, 0xffff0000, v40
	v_pk_fma_f32 v[6:7], v[6:7], v[22:23], v[2:3]
	v_cvt_pk_f16_f32 v2, v14, v15
	v_pk_fma_f32 v[14:15], v[114:115], v[14:15], s[42:43] op_sel_hi:[0,1,0]
	v_add_f32_e32 v84, v102, v84
	v_lshlrev_b32_e32 v24, 16, v39
	v_and_b32_e32 v25, 0xffff0000, v39
	v_med3_f32 v14, v14, s93, v221
	v_med3_f32 v15, v15, s93, v221
	v_rcp_f32_e32 v8, v8
	v_rcp_f32_e32 v9, v9
	v_pk_fma_f32 v[16:17], v[4:5], v[24:25], v[16:17]
	v_cvt_f32_f16_e32 v4, v49
	v_cvt_f32_f16_sdwa v5, v49 dst_sel:DWORD dst_unused:UNUSED_PAD src0_sel:WORD_1
	v_perm_b32 v14, v15, v14, s1
	ds_bpermute_b32 v15, v223, v84
	v_cvt_pk_f16_f32 v3, v16, v17
	v_pk_fma_f32 v[16:17], v[114:115], v[16:17], s[42:43] op_sel_hi:[0,1,0]
	v_lshlrev_b32_e32 v24, 16, v41
	v_and_b32_e32 v25, 0xffff0000, v41
	v_med3_f32 v16, v16, s93, v221
	v_med3_f32 v17, v17, s93, v221
	v_pk_fma_f32 v[8:9], v[8:9], v[24:25], v[4:5]
	v_cvt_pk_f16_f32 v4, v6, v7
	v_perm_b32 v16, v17, v16, s1
	v_pk_fma_f32 v[6:7], v[114:115], v[6:7], s[42:43] op_sel_hi:[0,1,0]
	v_perm_b32 v14, v16, v14, s51
	v_med3_f32 v16, v6, s93, v221
	s_waitcnt lgkmcnt(0)
	v_add_f32_e32 v6, v84, v15
	v_med3_f32 v17, v7, s93, v221
	ds_bpermute_b32 v7, v224, v6
	v_cvt_pk_f16_f32 v5, v8, v9
	v_pk_fma_f32 v[8:9], v[114:115], v[8:9], s[42:43] op_sel_hi:[0,1,0]
	v_med3_f32 v8, v8, s93, v221
	v_med3_f32 v9, v9, s93, v221
	v_perm_b32 v8, v9, v8, s1
	v_perm_b32 v9, v17, v16, s1
	v_perm_b32 v15, v8, v9, s51
	global_store_dwordx4 v[72:73], v[2:5], off offset:256
	global_store_dwordx2 v[70:71], v[14:15], off offset:128
	s_and_saveexec_b64 s[26:27], s[4:5]
	s_cbranch_execz .LBB0_1628
	s_waitcnt lgkmcnt(0)
	v_add_f32_e32 v6, v6, v7
	v_fma_f32 v6, v6, s33, 0.5
	v_trunc_f32_e32 v6, v6
	v_mul_f32_e32 v7, 0x2f800000, v6
	v_floor_f32_e32 v7, v7
	v_fmac_f32_e32 v6, 0xcf800000, v7
	v_cvt_u32_f32_e32 v6, v6
	v_cvt_u32_f32_e32 v7, v7
	v_lshl_add_u64 v[8:9], v[112:113], 3, s[18:19]
	global_atomic_add_x2 v[8:9], v[6:7], off
